# snake order over the four x fragments per y fragment (y-major) of the chained MFMA pairs across the whole 32-MFMA super-phase, all live bf16 K-loops
# baseline (speedup 1.0000x reference)
.LBB0_1516:
	v_add_u32_e32 v156, s83, v142
	v_add_u32_e32 v172, s44, v142
	s_add_u32 s8, s37, s6
	ds_read_b128 v[144:147], v156
	ds_read_b128 v[148:151], v156 offset:1024
	ds_read_b128 v[152:155], v156 offset:2048
	ds_read_b128 v[156:159], v156 offset:3072
	ds_read_b128 v[160:163], v172
	ds_read_b128 v[164:167], v172 offset:1024
	ds_read_b128 v[168:171], v172 offset:2048
	ds_read_b128 v[172:175], v172 offset:3072
	s_addc_u32 s9, s40, s7
	s_add_u32 s8, s8, 0x20400100
	s_addc_u32 s9, s9, 0
	s_add_u32 s46, s41, s6
	s_addc_u32 s47, s42, s7
	s_cmpk_eq_i32 s6, 0xf00
	s_cselect_b32 s11, s5, s9
	s_cselect_b32 s10, s4, s8
	s_cselect_b32 s9, s3, s47
	s_cselect_b32 s8, s2, s46
	v_lshl_add_u64 v[208:209], v[138:139], 0, s[6:7]
	s_add_i32 m0, s16, 0xc000
	ds_read_b128 v[176:179], v143
	ds_read_b128 v[180:183], v143 offset:1024
	ds_read_b128 v[184:187], v143 offset:2048
	ds_read_b128 v[188:191], v143 offset:3072
	ds_read_b128 v[192:195], v143 offset:4096
	ds_read_b128 v[196:199], v143 offset:5120
	ds_read_b128 v[200:203], v143 offset:6144
	ds_read_b128 v[204:207], v143 offset:7168
	global_load_lds_dwordx4 v[208:209], off
	v_lshl_add_u64 v[208:209], v[140:141], 0, s[6:7]
	s_add_i32 m0, s16, 0xe000
	s_nop 0
	global_load_lds_dwordx4 v[208:209], off
	s_waitcnt vmcnt(8)
	s_waitcnt lgkmcnt(0)
	s_barrier
	s_setprio 1
	s_waitcnt lgkmcnt(0)
	v_mfma_f32_16x16x32_bf16 v[128:131], v[144:147], v[176:179], v[128:131]
	v_mfma_f32_16x16x32_bf16 v[128:131], v[148:151], v[180:183], v[128:131]
	v_mfma_f32_16x16x32_bf16 v[124:127], v[152:155], v[176:179], v[124:127]
	v_mfma_f32_16x16x32_bf16 v[124:127], v[156:159], v[180:183], v[124:127]
	v_mfma_f32_16x16x32_bf16 v[120:123], v[160:163], v[176:179], v[120:123]
	v_mfma_f32_16x16x32_bf16 v[120:123], v[164:167], v[180:183], v[120:123]
	v_mfma_f32_16x16x32_bf16 v[116:119], v[168:171], v[176:179], v[116:119]
	v_mfma_f32_16x16x32_bf16 v[116:119], v[172:175], v[180:183], v[116:119]
	v_mfma_f32_16x16x32_bf16 v[100:103], v[168:171], v[184:187], v[100:103]
	v_mfma_f32_16x16x32_bf16 v[100:103], v[172:175], v[188:191], v[100:103]
	v_mfma_f32_16x16x32_bf16 v[104:107], v[160:163], v[184:187], v[104:107]
	v_mfma_f32_16x16x32_bf16 v[104:107], v[164:167], v[188:191], v[104:107]
	v_mfma_f32_16x16x32_bf16 v[108:111], v[152:155], v[184:187], v[108:111]
	v_mfma_f32_16x16x32_bf16 v[108:111], v[156:159], v[188:191], v[108:111]
	v_mfma_f32_16x16x32_bf16 v[112:115], v[144:147], v[184:187], v[112:115]
	v_mfma_f32_16x16x32_bf16 v[112:115], v[148:151], v[188:191], v[112:115]
	s_setprio 0
	s_setprio 1
	v_mfma_f32_16x16x32_bf16 v[96:99], v[144:147], v[192:195], v[96:99]
	v_mfma_f32_16x16x32_bf16 v[96:99], v[148:151], v[196:199], v[96:99]
	v_mfma_f32_16x16x32_bf16 v[92:95], v[152:155], v[192:195], v[92:95]
	v_mfma_f32_16x16x32_bf16 v[92:95], v[156:159], v[196:199], v[92:95]
	v_mfma_f32_16x16x32_bf16 v[88:91], v[160:163], v[192:195], v[88:91]
	v_mfma_f32_16x16x32_bf16 v[88:91], v[164:167], v[196:199], v[88:91]
	v_mfma_f32_16x16x32_bf16 v[84:87], v[168:171], v[192:195], v[84:87]
	v_mfma_f32_16x16x32_bf16 v[84:87], v[172:175], v[196:199], v[84:87]
	v_mfma_f32_16x16x32_bf16 v[68:71], v[168:171], v[200:203], v[68:71]
	v_mfma_f32_16x16x32_bf16 v[68:71], v[172:175], v[204:207], v[68:71]
	v_mfma_f32_16x16x32_bf16 v[72:75], v[160:163], v[200:203], v[72:75]
	v_mfma_f32_16x16x32_bf16 v[72:75], v[164:167], v[204:207], v[72:75]
	v_mfma_f32_16x16x32_bf16 v[76:79], v[152:155], v[200:203], v[76:79]
	v_mfma_f32_16x16x32_bf16 v[76:79], v[156:159], v[204:207], v[76:79]
	v_mfma_f32_16x16x32_bf16 v[80:83], v[144:147], v[200:203], v[80:83]
	v_mfma_f32_16x16x32_bf16 v[80:83], v[148:151], v[204:207], v[80:83]
	s_setprio 0
	s_barrier
	s_mov_b32 m0, s13
	v_lshl_add_u64 v[208:209], s[8:9], 0, v[2:3]
	s_add_u32 s46, s8, 0x80000
	ds_read_b128 v[176:179], v143 offset:16384
	ds_read_b128 v[180:183], v143 offset:17408
	ds_read_b128 v[184:187], v143 offset:18432
	ds_read_b128 v[188:191], v143 offset:19456
	ds_read_b128 v[192:195], v143 offset:20480
	ds_read_b128 v[196:199], v143 offset:21504
	ds_read_b128 v[200:203], v143 offset:22528
	ds_read_b128 v[204:207], v143 offset:23552
	global_load_lds_dwordx4 v[208:209], off
	v_lshl_add_u64 v[210:211], s[8:9], 0, v[136:137]
	s_mov_b32 m0, s14
	s_addc_u32 s47, s9, 0
	global_load_lds_dwordx4 v[210:211], off
	v_lshl_add_u64 v[216:217], s[46:47], 0, v[2:3]
	s_mov_b32 m0, s15
	v_lshl_add_u64 v[218:219], s[10:11], 0, v[134:135]
	global_load_lds_dwordx4 v[216:217], off
	v_lshl_add_u64 v[216:217], s[46:47], 0, v[136:137]
	s_mov_b32 m0, s19
	s_nop 0
	global_load_lds_dwordx4 v[216:217], off
	v_lshl_add_u64 v[216:217], s[10:11], 0, v[132:133]
	s_mov_b32 m0, s16
	s_nop 0
	global_load_lds_dwordx4 v[216:217], off
	s_mov_b32 m0, s20
	s_nop 0
	global_load_lds_dwordx4 v[218:219], off
	s_waitcnt vmcnt(8)
	s_waitcnt lgkmcnt(0)
	s_barrier
	s_setprio 1
	s_waitcnt lgkmcnt(0)
	v_mfma_f32_16x16x32_bf16 v[64:67], v[144:147], v[176:179], v[64:67]
	v_mfma_f32_16x16x32_bf16 v[64:67], v[148:151], v[180:183], v[64:67]
	v_mfma_f32_16x16x32_bf16 v[60:63], v[152:155], v[176:179], v[60:63]
	v_mfma_f32_16x16x32_bf16 v[60:63], v[156:159], v[180:183], v[60:63]
	v_mfma_f32_16x16x32_bf16 v[56:59], v[160:163], v[176:179], v[56:59]
	v_mfma_f32_16x16x32_bf16 v[56:59], v[164:167], v[180:183], v[56:59]
	v_mfma_f32_16x16x32_bf16 v[52:55], v[168:171], v[176:179], v[52:55]
	v_mfma_f32_16x16x32_bf16 v[52:55], v[172:175], v[180:183], v[52:55]
	v_mfma_f32_16x16x32_bf16 v[36:39], v[168:171], v[184:187], v[36:39]
	v_mfma_f32_16x16x32_bf16 v[36:39], v[172:175], v[188:191], v[36:39]
	v_mfma_f32_16x16x32_bf16 v[40:43], v[160:163], v[184:187], v[40:43]
	v_mfma_f32_16x16x32_bf16 v[40:43], v[164:167], v[188:191], v[40:43]
	v_mfma_f32_16x16x32_bf16 v[44:47], v[152:155], v[184:187], v[44:47]
	v_mfma_f32_16x16x32_bf16 v[44:47], v[156:159], v[188:191], v[44:47]
	v_mfma_f32_16x16x32_bf16 v[48:51], v[144:147], v[184:187], v[48:51]
	v_mfma_f32_16x16x32_bf16 v[48:51], v[148:151], v[188:191], v[48:51]
	s_setprio 0
	s_setprio 1
	v_mfma_f32_16x16x32_bf16 v[32:35], v[144:147], v[192:195], v[32:35]
	v_mfma_f32_16x16x32_bf16 v[32:35], v[148:151], v[196:199], v[32:35]
	v_mfma_f32_16x16x32_bf16 v[28:31], v[152:155], v[192:195], v[28:31]
	v_mfma_f32_16x16x32_bf16 v[28:31], v[156:159], v[196:199], v[28:31]
	v_mfma_f32_16x16x32_bf16 v[24:27], v[160:163], v[192:195], v[24:27]
	v_mfma_f32_16x16x32_bf16 v[24:27], v[164:167], v[196:199], v[24:27]
	v_mfma_f32_16x16x32_bf16 v[20:23], v[168:171], v[192:195], v[20:23]
	v_mfma_f32_16x16x32_bf16 v[20:23], v[172:175], v[196:199], v[20:23]
	v_mfma_f32_16x16x32_bf16 v[4:7], v[168:171], v[200:203], v[4:7]
	v_mfma_f32_16x16x32_bf16 v[4:7], v[172:175], v[204:207], v[4:7]
	v_mfma_f32_16x16x32_bf16 v[8:11], v[160:163], v[200:203], v[8:11]
	v_mfma_f32_16x16x32_bf16 v[8:11], v[164:167], v[204:207], v[8:11]
	v_mfma_f32_16x16x32_bf16 v[12:15], v[152:155], v[200:203], v[12:15]
	v_mfma_f32_16x16x32_bf16 v[12:15], v[156:159], v[204:207], v[12:15]
	v_mfma_f32_16x16x32_bf16 v[16:19], v[144:147], v[200:203], v[16:19]
	v_mfma_f32_16x16x32_bf16 v[16:19], v[148:151], v[204:207], v[16:19]
	s_setprio 0
	s_barrier
	v_add_u32_e32 v156, s45, v142
	v_add_u32_e32 v172, s74, v142
	ds_read_b128 v[144:147], v156
	ds_read_b128 v[148:151], v156 offset:1024
	ds_read_b128 v[152:155], v156 offset:2048
	ds_read_b128 v[156:159], v156 offset:3072
	ds_read_b128 v[160:163], v172
	ds_read_b128 v[164:167], v172 offset:1024
	ds_read_b128 v[168:171], v172 offset:2048
	ds_read_b128 v[172:175], v172 offset:3072
	s_add_u32 s10, s10, 0x80000
	s_addc_u32 s11, s11, 0
	s_mov_b32 m0, s22
	v_lshl_add_u64 v[220:221], s[10:11], 0, v[132:133]
	ds_read_b128 v[176:179], v143 offset:32768
	ds_read_b128 v[180:183], v143 offset:33792
	ds_read_b128 v[184:187], v143 offset:34816
	ds_read_b128 v[188:191], v143 offset:35840
	ds_read_b128 v[192:195], v143 offset:36864
	ds_read_b128 v[196:199], v143 offset:37888
	ds_read_b128 v[200:203], v143 offset:38912
	ds_read_b128 v[204:207], v143 offset:39936
	global_load_lds_dwordx4 v[220:221], off
	v_lshl_add_u64 v[220:221], s[10:11], 0, v[134:135]
	s_mov_b32 m0, s23
	s_nop 0
	global_load_lds_dwordx4 v[220:221], off
	s_waitcnt vmcnt(8)
	s_waitcnt lgkmcnt(0)
	s_barrier
	s_setprio 1
	s_waitcnt lgkmcnt(0)
	v_mfma_f32_16x16x32_bf16 v[128:131], v[144:147], v[176:179], v[128:131]
	v_mfma_f32_16x16x32_bf16 v[128:131], v[148:151], v[180:183], v[128:131]
	v_mfma_f32_16x16x32_bf16 v[124:127], v[152:155], v[176:179], v[124:127]
	v_mfma_f32_16x16x32_bf16 v[124:127], v[156:159], v[180:183], v[124:127]
	v_mfma_f32_16x16x32_bf16 v[120:123], v[160:163], v[176:179], v[120:123]
	v_mfma_f32_16x16x32_bf16 v[120:123], v[164:167], v[180:183], v[120:123]
	v_mfma_f32_16x16x32_bf16 v[116:119], v[168:171], v[176:179], v[116:119]
	v_mfma_f32_16x16x32_bf16 v[116:119], v[172:175], v[180:183], v[116:119]
	v_mfma_f32_16x16x32_bf16 v[100:103], v[168:171], v[184:187], v[100:103]
	v_mfma_f32_16x16x32_bf16 v[100:103], v[172:175], v[188:191], v[100:103]
	v_mfma_f32_16x16x32_bf16 v[104:107], v[160:163], v[184:187], v[104:107]
	v_mfma_f32_16x16x32_bf16 v[104:107], v[164:167], v[188:191], v[104:107]
	v_mfma_f32_16x16x32_bf16 v[108:111], v[152:155], v[184:187], v[108:111]
	v_mfma_f32_16x16x32_bf16 v[108:111], v[156:159], v[188:191], v[108:111]
	v_mfma_f32_16x16x32_bf16 v[112:115], v[144:147], v[184:187], v[112:115]
	v_mfma_f32_16x16x32_bf16 v[112:115], v[148:151], v[188:191], v[112:115]
	s_setprio 0
	s_setprio 1
	v_mfma_f32_16x16x32_bf16 v[96:99], v[144:147], v[192:195], v[96:99]
	v_mfma_f32_16x16x32_bf16 v[96:99], v[148:151], v[196:199], v[96:99]
	v_mfma_f32_16x16x32_bf16 v[92:95], v[152:155], v[192:195], v[92:95]
	v_mfma_f32_16x16x32_bf16 v[92:95], v[156:159], v[196:199], v[92:95]
	v_mfma_f32_16x16x32_bf16 v[88:91], v[160:163], v[192:195], v[88:91]
	v_mfma_f32_16x16x32_bf16 v[88:91], v[164:167], v[196:199], v[88:91]
	v_mfma_f32_16x16x32_bf16 v[84:87], v[168:171], v[192:195], v[84:87]
	v_mfma_f32_16x16x32_bf16 v[84:87], v[172:175], v[196:199], v[84:87]
	v_mfma_f32_16x16x32_bf16 v[68:71], v[168:171], v[200:203], v[68:71]
	v_mfma_f32_16x16x32_bf16 v[68:71], v[172:175], v[204:207], v[68:71]
	v_mfma_f32_16x16x32_bf16 v[72:75], v[160:163], v[200:203], v[72:75]
	v_mfma_f32_16x16x32_bf16 v[72:75], v[164:167], v[204:207], v[72:75]
	v_mfma_f32_16x16x32_bf16 v[76:79], v[152:155], v[200:203], v[76:79]
	v_mfma_f32_16x16x32_bf16 v[76:79], v[156:159], v[204:207], v[76:79]
	v_mfma_f32_16x16x32_bf16 v[80:83], v[144:147], v[200:203], v[80:83]
	v_mfma_f32_16x16x32_bf16 v[80:83], v[148:151], v[204:207], v[80:83]
	s_setprio 0
	s_barrier
	s_mov_b32 m0, s24
	v_lshl_add_u64 v[208:209], v[208:209], 0, s[64:65]
	s_add_u32 s8, s8, 0x80080
	ds_read_b128 v[176:179], v143 offset:49152
	ds_read_b128 v[180:183], v143 offset:50176
	ds_read_b128 v[184:187], v143 offset:51200
	ds_read_b128 v[188:191], v143 offset:52224
	ds_read_b128 v[192:195], v143 offset:53248
	ds_read_b128 v[196:199], v143 offset:54272
	ds_read_b128 v[200:203], v143 offset:55296
	ds_read_b128 v[204:207], v143 offset:56320
	global_load_lds_dwordx4 v[208:209], off
	v_lshl_add_u64 v[208:209], v[210:211], 0, s[64:65]
	s_mov_b32 m0, s25
	s_addc_u32 s9, s9, 0
	global_load_lds_dwordx4 v[208:209], off
	v_lshl_add_u64 v[208:209], s[8:9], 0, v[2:3]
	s_mov_b32 m0, s34
	s_nop 0
	global_load_lds_dwordx4 v[208:209], off
	v_lshl_add_u64 v[208:209], s[8:9], 0, v[136:137]
	s_mov_b32 m0, s35
	s_nop 0
	global_load_lds_dwordx4 v[208:209], off
	v_lshl_add_u64 v[208:209], v[216:217], 0, s[64:65]
	s_mov_b32 m0, s26
	s_nop 0
	global_load_lds_dwordx4 v[208:209], off
	v_lshl_add_u64 v[208:209], v[218:219], 0, s[64:65]
	s_mov_b32 m0, s27
	s_nop 0
	global_load_lds_dwordx4 v[208:209], off
	s_waitcnt vmcnt(8)
	s_waitcnt lgkmcnt(0)
	s_barrier
	s_setprio 1
	s_waitcnt lgkmcnt(0)
	v_mfma_f32_16x16x32_bf16 v[64:67], v[144:147], v[176:179], v[64:67]
	v_mfma_f32_16x16x32_bf16 v[64:67], v[148:151], v[180:183], v[64:67]
	v_mfma_f32_16x16x32_bf16 v[60:63], v[152:155], v[176:179], v[60:63]
	v_mfma_f32_16x16x32_bf16 v[60:63], v[156:159], v[180:183], v[60:63]
	v_mfma_f32_16x16x32_bf16 v[56:59], v[160:163], v[176:179], v[56:59]
	v_mfma_f32_16x16x32_bf16 v[56:59], v[164:167], v[180:183], v[56:59]
	v_mfma_f32_16x16x32_bf16 v[52:55], v[168:171], v[176:179], v[52:55]
	v_mfma_f32_16x16x32_bf16 v[52:55], v[172:175], v[180:183], v[52:55]
	v_mfma_f32_16x16x32_bf16 v[36:39], v[168:171], v[184:187], v[36:39]
	v_mfma_f32_16x16x32_bf16 v[36:39], v[172:175], v[188:191], v[36:39]
	v_mfma_f32_16x16x32_bf16 v[40:43], v[160:163], v[184:187], v[40:43]
	v_mfma_f32_16x16x32_bf16 v[40:43], v[164:167], v[188:191], v[40:43]
	v_mfma_f32_16x16x32_bf16 v[44:47], v[152:155], v[184:187], v[44:47]
	v_mfma_f32_16x16x32_bf16 v[44:47], v[156:159], v[188:191], v[44:47]
	v_mfma_f32_16x16x32_bf16 v[48:51], v[144:147], v[184:187], v[48:51]
	v_mfma_f32_16x16x32_bf16 v[48:51], v[148:151], v[188:191], v[48:51]
	s_setprio 0
	s_setprio 1
	v_mfma_f32_16x16x32_bf16 v[32:35], v[144:147], v[192:195], v[32:35]
	v_mfma_f32_16x16x32_bf16 v[32:35], v[148:151], v[196:199], v[32:35]
	v_mfma_f32_16x16x32_bf16 v[28:31], v[152:155], v[192:195], v[28:31]
	v_mfma_f32_16x16x32_bf16 v[28:31], v[156:159], v[196:199], v[28:31]
	v_mfma_f32_16x16x32_bf16 v[24:27], v[160:163], v[192:195], v[24:27]
	v_mfma_f32_16x16x32_bf16 v[24:27], v[164:167], v[196:199], v[24:27]
	v_mfma_f32_16x16x32_bf16 v[20:23], v[168:171], v[192:195], v[20:23]
	v_mfma_f32_16x16x32_bf16 v[20:23], v[172:175], v[196:199], v[20:23]
	v_mfma_f32_16x16x32_bf16 v[4:7], v[168:171], v[200:203], v[4:7]
	v_mfma_f32_16x16x32_bf16 v[4:7], v[172:175], v[204:207], v[4:7]
	v_mfma_f32_16x16x32_bf16 v[8:11], v[160:163], v[200:203], v[8:11]
	v_mfma_f32_16x16x32_bf16 v[8:11], v[164:167], v[204:207], v[8:11]
	v_mfma_f32_16x16x32_bf16 v[12:15], v[152:155], v[200:203], v[12:15]
	v_mfma_f32_16x16x32_bf16 v[12:15], v[156:159], v[204:207], v[12:15]
	v_mfma_f32_16x16x32_bf16 v[16:19], v[144:147], v[200:203], v[16:19]
	v_mfma_f32_16x16x32_bf16 v[16:19], v[148:151], v[204:207], v[16:19]
	s_setprio 0
	s_barrier
	s_add_i32 s43, s43, 2
	s_add_u32 s6, s6, 0x100
	s_addc_u32 s7, s7, 0
	s_cmp_gt_u32 s43, 29
	s_cbranch_scc0 .LBB0_1516
	s_cmpk_lt_u32 s21, 0x100
	s_cbranch_scc0 .LBB0_1519
	s_barrier

.LBB0_1876:
	v_add_u32_e32 v2, s83, v144
	ds_read_b128 v[146:149], v2
	ds_read_b128 v[150:153], v2 offset:1024
	ds_read_b128 v[154:157], v2 offset:2048
	ds_read_b128 v[158:161], v2 offset:3072
	v_add_u32_e32 v2, s44, v144
	ds_read_b128 v[162:165], v2
	ds_read_b128 v[166:169], v2 offset:1024
	ds_read_b128 v[170:173], v2 offset:2048
	ds_read_b128 v[174:177], v2 offset:3072
	s_add_i32 s70, s18, 2
	s_add_u32 s71, s42, 0x80
	s_addc_u32 s19, s43, 0
	s_cmp_eq_u32 s57, s18
	s_cselect_b32 s18, s34, s71
	s_cselect_b32 s19, s35, s19
	s_cselect_b32 s77, s25, s69
	s_cselect_b32 s76, s24, s68
	v_lshl_add_u64 v[210:211], s[42:43], 0, v[140:141]
	s_add_i32 m0, s23, 0xc000
	ds_read_b128 v[178:181], v145
	ds_read_b128 v[182:185], v145 offset:1024
	ds_read_b128 v[186:189], v145 offset:2048
	ds_read_b128 v[190:193], v145 offset:3072
	ds_read_b128 v[194:197], v145 offset:4096
	ds_read_b128 v[198:201], v145 offset:5120
	ds_read_b128 v[202:205], v145 offset:6144
	ds_read_b128 v[206:209], v145 offset:7168
	global_load_lds_dwordx4 v[210:211], off
	v_lshl_add_u64 v[210:211], s[42:43], 0, v[142:143]
	s_add_i32 m0, s23, 0xe000
	s_nop 0
	global_load_lds_dwordx4 v[210:211], off
	s_waitcnt vmcnt(8)
	s_waitcnt lgkmcnt(0)
	s_barrier
	s_setprio 1
	s_waitcnt lgkmcnt(0)
	v_mfma_f32_16x16x32_bf16 v[120:123], v[146:149], v[178:181], v[120:123]
	v_mfma_f32_16x16x32_bf16 v[120:123], v[150:153], v[182:185], v[120:123]
	v_mfma_f32_16x16x32_bf16 v[128:131], v[154:157], v[178:181], v[128:131]
	v_mfma_f32_16x16x32_bf16 v[128:131], v[158:161], v[182:185], v[128:131]
	v_mfma_f32_16x16x32_bf16 v[124:127], v[162:165], v[178:181], v[124:127]
	v_mfma_f32_16x16x32_bf16 v[124:127], v[166:169], v[182:185], v[124:127]
	v_mfma_f32_16x16x32_bf16 v[116:119], v[170:173], v[178:181], v[116:119]
	v_mfma_f32_16x16x32_bf16 v[116:119], v[174:177], v[182:185], v[116:119]
	v_mfma_f32_16x16x32_bf16 v[100:103], v[170:173], v[186:189], v[100:103]
	v_mfma_f32_16x16x32_bf16 v[100:103], v[174:177], v[190:193], v[100:103]
	v_mfma_f32_16x16x32_bf16 v[104:107], v[162:165], v[186:189], v[104:107]
	v_mfma_f32_16x16x32_bf16 v[104:107], v[166:169], v[190:193], v[104:107]
	v_mfma_f32_16x16x32_bf16 v[108:111], v[154:157], v[186:189], v[108:111]
	v_mfma_f32_16x16x32_bf16 v[108:111], v[158:161], v[190:193], v[108:111]
	v_mfma_f32_16x16x32_bf16 v[112:115], v[146:149], v[186:189], v[112:115]
	v_mfma_f32_16x16x32_bf16 v[112:115], v[150:153], v[190:193], v[112:115]
	s_setprio 0
	s_setprio 1
	v_mfma_f32_16x16x32_bf16 v[96:99], v[146:149], v[194:197], v[96:99]
	v_mfma_f32_16x16x32_bf16 v[96:99], v[150:153], v[198:201], v[96:99]
	v_mfma_f32_16x16x32_bf16 v[92:95], v[154:157], v[194:197], v[92:95]
	v_mfma_f32_16x16x32_bf16 v[92:95], v[158:161], v[198:201], v[92:95]
	v_mfma_f32_16x16x32_bf16 v[88:91], v[162:165], v[194:197], v[88:91]
	v_mfma_f32_16x16x32_bf16 v[88:91], v[166:169], v[198:201], v[88:91]
	v_mfma_f32_16x16x32_bf16 v[84:87], v[170:173], v[194:197], v[84:87]
	v_mfma_f32_16x16x32_bf16 v[84:87], v[174:177], v[198:201], v[84:87]
	v_mfma_f32_16x16x32_bf16 v[68:71], v[170:173], v[202:205], v[68:71]
	v_mfma_f32_16x16x32_bf16 v[68:71], v[174:177], v[206:209], v[68:71]
	v_mfma_f32_16x16x32_bf16 v[72:75], v[162:165], v[202:205], v[72:75]
	v_mfma_f32_16x16x32_bf16 v[72:75], v[166:169], v[206:209], v[72:75]
	v_mfma_f32_16x16x32_bf16 v[76:79], v[154:157], v[202:205], v[76:79]
	v_mfma_f32_16x16x32_bf16 v[76:79], v[158:161], v[206:209], v[76:79]
	v_mfma_f32_16x16x32_bf16 v[80:83], v[146:149], v[202:205], v[80:83]
	v_mfma_f32_16x16x32_bf16 v[80:83], v[150:153], v[206:209], v[80:83]
	s_setprio 0
	s_barrier
	s_mov_b32 m0, s16
	v_lshl_add_u64 v[210:211], s[76:77], 0, v[134:135]
	v_lshl_add_u64 v[216:217], s[76:77], 0, v[138:139]
	s_add_u32 s76, s76, s4
	ds_read_b128 v[178:181], v145 offset:16384
	ds_read_b128 v[182:185], v145 offset:17408
	ds_read_b128 v[186:189], v145 offset:18432
	ds_read_b128 v[190:193], v145 offset:19456
	ds_read_b128 v[194:197], v145 offset:20480
	ds_read_b128 v[198:201], v145 offset:21504
	ds_read_b128 v[202:205], v145 offset:22528
	ds_read_b128 v[206:209], v145 offset:23552
	global_load_lds_dwordx4 v[210:211], off
	s_mov_b32 m0, s20
	s_addc_u32 s77, s77, s5
	global_load_lds_dwordx4 v[216:217], off
	v_lshl_add_u64 v[218:219], s[76:77], 0, v[134:135]
	s_mov_b32 m0, s21
	v_lshl_add_u64 v[220:221], s[76:77], 0, v[138:139]
	global_load_lds_dwordx4 v[218:219], off
	s_mov_b32 m0, s22
	v_lshl_add_u64 v[222:223], s[18:19], 0, v[132:133]
	global_load_lds_dwordx4 v[220:221], off
	s_mov_b32 m0, s23
	v_lshl_add_u64 v[224:225], s[18:19], 0, v[136:137]
	global_load_lds_dwordx4 v[222:223], off
	s_mov_b32 m0, s26
	s_nop 0
	global_load_lds_dwordx4 v[224:225], off
	s_waitcnt vmcnt(8)
	s_waitcnt lgkmcnt(0)
	s_barrier
	s_setprio 1
	s_waitcnt lgkmcnt(0)
	v_mfma_f32_16x16x32_bf16 v[64:67], v[146:149], v[178:181], v[64:67]
	v_mfma_f32_16x16x32_bf16 v[64:67], v[150:153], v[182:185], v[64:67]
	v_mfma_f32_16x16x32_bf16 v[60:63], v[154:157], v[178:181], v[60:63]
	v_mfma_f32_16x16x32_bf16 v[60:63], v[158:161], v[182:185], v[60:63]
	v_mfma_f32_16x16x32_bf16 v[56:59], v[162:165], v[178:181], v[56:59]
	v_mfma_f32_16x16x32_bf16 v[56:59], v[166:169], v[182:185], v[56:59]
	v_mfma_f32_16x16x32_bf16 v[52:55], v[170:173], v[178:181], v[52:55]
	v_mfma_f32_16x16x32_bf16 v[52:55], v[174:177], v[182:185], v[52:55]
	v_mfma_f32_16x16x32_bf16 v[36:39], v[170:173], v[186:189], v[36:39]
	v_mfma_f32_16x16x32_bf16 v[36:39], v[174:177], v[190:193], v[36:39]
	v_mfma_f32_16x16x32_bf16 v[40:43], v[162:165], v[186:189], v[40:43]
	v_mfma_f32_16x16x32_bf16 v[40:43], v[166:169], v[190:193], v[40:43]
	v_mfma_f32_16x16x32_bf16 v[44:47], v[154:157], v[186:189], v[44:47]
	v_mfma_f32_16x16x32_bf16 v[44:47], v[158:161], v[190:193], v[44:47]
	v_mfma_f32_16x16x32_bf16 v[48:51], v[146:149], v[186:189], v[48:51]
	v_mfma_f32_16x16x32_bf16 v[48:51], v[150:153], v[190:193], v[48:51]
	s_setprio 0
	s_setprio 1
	v_mfma_f32_16x16x32_bf16 v[32:35], v[146:149], v[194:197], v[32:35]
	v_mfma_f32_16x16x32_bf16 v[32:35], v[150:153], v[198:201], v[32:35]
	v_mfma_f32_16x16x32_bf16 v[28:31], v[154:157], v[194:197], v[28:31]
	v_mfma_f32_16x16x32_bf16 v[28:31], v[158:161], v[198:201], v[28:31]
	v_mfma_f32_16x16x32_bf16 v[24:27], v[162:165], v[194:197], v[24:27]
	v_mfma_f32_16x16x32_bf16 v[24:27], v[166:169], v[198:201], v[24:27]
	v_mfma_f32_16x16x32_bf16 v[20:23], v[170:173], v[194:197], v[20:23]
	v_mfma_f32_16x16x32_bf16 v[20:23], v[174:177], v[198:201], v[20:23]
	v_mfma_f32_16x16x32_bf16 v[4:7], v[170:173], v[202:205], v[4:7]
	v_mfma_f32_16x16x32_bf16 v[4:7], v[174:177], v[206:209], v[4:7]
	v_mfma_f32_16x16x32_bf16 v[8:11], v[162:165], v[202:205], v[8:11]
	v_mfma_f32_16x16x32_bf16 v[8:11], v[166:169], v[206:209], v[8:11]
	v_mfma_f32_16x16x32_bf16 v[12:15], v[154:157], v[202:205], v[12:15]
	v_mfma_f32_16x16x32_bf16 v[12:15], v[158:161], v[206:209], v[12:15]
	v_mfma_f32_16x16x32_bf16 v[16:19], v[146:149], v[202:205], v[16:19]
	v_mfma_f32_16x16x32_bf16 v[16:19], v[150:153], v[206:209], v[16:19]
	s_setprio 0
	s_barrier
	v_add_u32_e32 v2, s45, v144
	ds_read_b128 v[146:149], v2
	ds_read_b128 v[150:153], v2 offset:1024
	ds_read_b128 v[154:157], v2 offset:2048
	ds_read_b128 v[158:161], v2 offset:3072
	v_add_u32_e32 v2, s74, v144
	ds_read_b128 v[162:165], v2
	ds_read_b128 v[166:169], v2 offset:1024
	ds_read_b128 v[170:173], v2 offset:2048
	ds_read_b128 v[174:177], v2 offset:3072
	s_add_u32 s18, s18, s4
	s_addc_u32 s19, s19, s5
	s_mov_b32 m0, s27
	v_lshl_add_u64 v[226:227], s[18:19], 0, v[132:133]
	ds_read_b128 v[178:181], v145 offset:32768
	ds_read_b128 v[182:185], v145 offset:33792
	ds_read_b128 v[186:189], v145 offset:34816
	ds_read_b128 v[190:193], v145 offset:35840
	ds_read_b128 v[194:197], v145 offset:36864
	ds_read_b128 v[198:201], v145 offset:37888
	ds_read_b128 v[202:205], v145 offset:38912
	ds_read_b128 v[206:209], v145 offset:39936
	global_load_lds_dwordx4 v[226:227], off
	v_lshl_add_u64 v[226:227], s[18:19], 0, v[136:137]
	s_mov_b32 m0, s37
	s_nop 0
	global_load_lds_dwordx4 v[226:227], off
	s_waitcnt vmcnt(8)
	s_waitcnt lgkmcnt(0)
	s_barrier
	s_setprio 1
	s_waitcnt lgkmcnt(0)
	v_mfma_f32_16x16x32_bf16 v[120:123], v[146:149], v[178:181], v[120:123]
	v_mfma_f32_16x16x32_bf16 v[120:123], v[150:153], v[182:185], v[120:123]
	v_mfma_f32_16x16x32_bf16 v[128:131], v[154:157], v[178:181], v[128:131]
	v_mfma_f32_16x16x32_bf16 v[128:131], v[158:161], v[182:185], v[128:131]
	v_mfma_f32_16x16x32_bf16 v[124:127], v[162:165], v[178:181], v[124:127]
	v_mfma_f32_16x16x32_bf16 v[124:127], v[166:169], v[182:185], v[124:127]
	v_mfma_f32_16x16x32_bf16 v[116:119], v[170:173], v[178:181], v[116:119]
	v_mfma_f32_16x16x32_bf16 v[116:119], v[174:177], v[182:185], v[116:119]
	v_mfma_f32_16x16x32_bf16 v[100:103], v[170:173], v[186:189], v[100:103]
	v_mfma_f32_16x16x32_bf16 v[100:103], v[174:177], v[190:193], v[100:103]
	v_mfma_f32_16x16x32_bf16 v[104:107], v[162:165], v[186:189], v[104:107]
	v_mfma_f32_16x16x32_bf16 v[104:107], v[166:169], v[190:193], v[104:107]
	v_mfma_f32_16x16x32_bf16 v[108:111], v[154:157], v[186:189], v[108:111]
	v_mfma_f32_16x16x32_bf16 v[108:111], v[158:161], v[190:193], v[108:111]
	v_mfma_f32_16x16x32_bf16 v[112:115], v[146:149], v[186:189], v[112:115]
	v_mfma_f32_16x16x32_bf16 v[112:115], v[150:153], v[190:193], v[112:115]
	s_setprio 0
	s_setprio 1
	v_mfma_f32_16x16x32_bf16 v[96:99], v[146:149], v[194:197], v[96:99]
	v_mfma_f32_16x16x32_bf16 v[96:99], v[150:153], v[198:201], v[96:99]
	v_mfma_f32_16x16x32_bf16 v[92:95], v[154:157], v[194:197], v[92:95]
	v_mfma_f32_16x16x32_bf16 v[92:95], v[158:161], v[198:201], v[92:95]
	v_mfma_f32_16x16x32_bf16 v[88:91], v[162:165], v[194:197], v[88:91]
	v_mfma_f32_16x16x32_bf16 v[88:91], v[166:169], v[198:201], v[88:91]
	v_mfma_f32_16x16x32_bf16 v[84:87], v[170:173], v[194:197], v[84:87]
	v_mfma_f32_16x16x32_bf16 v[84:87], v[174:177], v[198:201], v[84:87]
	v_mfma_f32_16x16x32_bf16 v[68:71], v[170:173], v[202:205], v[68:71]
	v_mfma_f32_16x16x32_bf16 v[68:71], v[174:177], v[206:209], v[68:71]
	v_mfma_f32_16x16x32_bf16 v[72:75], v[162:165], v[202:205], v[72:75]
	v_mfma_f32_16x16x32_bf16 v[72:75], v[166:169], v[206:209], v[72:75]
	v_mfma_f32_16x16x32_bf16 v[76:79], v[154:157], v[202:205], v[76:79]
	v_mfma_f32_16x16x32_bf16 v[76:79], v[158:161], v[206:209], v[76:79]
	v_mfma_f32_16x16x32_bf16 v[80:83], v[146:149], v[202:205], v[80:83]
	v_mfma_f32_16x16x32_bf16 v[80:83], v[150:153], v[206:209], v[80:83]
	s_setprio 0
	s_barrier
	s_mov_b32 m0, s49
	v_lshl_add_u64 v[210:211], v[210:211], 0, s[64:65]
	ds_read_b128 v[178:181], v145 offset:49152
	ds_read_b128 v[182:185], v145 offset:50176
	ds_read_b128 v[186:189], v145 offset:51200
	ds_read_b128 v[190:193], v145 offset:52224
	ds_read_b128 v[194:197], v145 offset:53248
	ds_read_b128 v[198:201], v145 offset:54272
	ds_read_b128 v[202:205], v145 offset:55296
	ds_read_b128 v[206:209], v145 offset:56320
	global_load_lds_dwordx4 v[210:211], off
	v_lshl_add_u64 v[210:211], v[216:217], 0, s[64:65]
	s_mov_b32 m0, s50
	s_nop 0
	global_load_lds_dwordx4 v[210:211], off
	v_lshl_add_u64 v[210:211], v[218:219], 0, s[64:65]
	s_mov_b32 m0, s53
	s_nop 0
	global_load_lds_dwordx4 v[210:211], off
	v_lshl_add_u64 v[210:211], v[220:221], 0, s[64:65]
	s_mov_b32 m0, s56
	s_nop 0
	global_load_lds_dwordx4 v[210:211], off
	v_lshl_add_u64 v[210:211], v[222:223], 0, s[64:65]
	s_mov_b32 m0, s51
	s_nop 0
	global_load_lds_dwordx4 v[210:211], off
	v_lshl_add_u64 v[210:211], v[224:225], 0, s[64:65]
	s_mov_b32 m0, s52
	s_nop 0
	global_load_lds_dwordx4 v[210:211], off
	s_waitcnt vmcnt(8)
	s_waitcnt lgkmcnt(0)
	s_barrier
	s_setprio 1
	s_waitcnt lgkmcnt(0)
	v_mfma_f32_16x16x32_bf16 v[64:67], v[146:149], v[178:181], v[64:67]
	v_mfma_f32_16x16x32_bf16 v[64:67], v[150:153], v[182:185], v[64:67]
	v_mfma_f32_16x16x32_bf16 v[60:63], v[154:157], v[178:181], v[60:63]
	v_mfma_f32_16x16x32_bf16 v[60:63], v[158:161], v[182:185], v[60:63]
	v_mfma_f32_16x16x32_bf16 v[56:59], v[162:165], v[178:181], v[56:59]
	v_mfma_f32_16x16x32_bf16 v[56:59], v[166:169], v[182:185], v[56:59]
	v_mfma_f32_16x16x32_bf16 v[52:55], v[170:173], v[178:181], v[52:55]
	v_mfma_f32_16x16x32_bf16 v[52:55], v[174:177], v[182:185], v[52:55]
	v_mfma_f32_16x16x32_bf16 v[36:39], v[170:173], v[186:189], v[36:39]
	v_mfma_f32_16x16x32_bf16 v[36:39], v[174:177], v[190:193], v[36:39]
	v_mfma_f32_16x16x32_bf16 v[40:43], v[162:165], v[186:189], v[40:43]
	v_mfma_f32_16x16x32_bf16 v[40:43], v[166:169], v[190:193], v[40:43]
	v_mfma_f32_16x16x32_bf16 v[44:47], v[154:157], v[186:189], v[44:47]
	v_mfma_f32_16x16x32_bf16 v[44:47], v[158:161], v[190:193], v[44:47]
	v_mfma_f32_16x16x32_bf16 v[48:51], v[146:149], v[186:189], v[48:51]
	v_mfma_f32_16x16x32_bf16 v[48:51], v[150:153], v[190:193], v[48:51]
	s_setprio 0
	s_setprio 1
	v_mfma_f32_16x16x32_bf16 v[32:35], v[146:149], v[194:197], v[32:35]
	v_mfma_f32_16x16x32_bf16 v[32:35], v[150:153], v[198:201], v[32:35]
	v_mfma_f32_16x16x32_bf16 v[28:31], v[154:157], v[194:197], v[28:31]
	v_mfma_f32_16x16x32_bf16 v[28:31], v[158:161], v[198:201], v[28:31]
	v_mfma_f32_16x16x32_bf16 v[24:27], v[162:165], v[194:197], v[24:27]
	v_mfma_f32_16x16x32_bf16 v[24:27], v[166:169], v[198:201], v[24:27]
	v_mfma_f32_16x16x32_bf16 v[20:23], v[170:173], v[194:197], v[20:23]
	v_mfma_f32_16x16x32_bf16 v[20:23], v[174:177], v[198:201], v[20:23]
	v_mfma_f32_16x16x32_bf16 v[4:7], v[170:173], v[202:205], v[4:7]
	v_mfma_f32_16x16x32_bf16 v[4:7], v[174:177], v[206:209], v[4:7]
	v_mfma_f32_16x16x32_bf16 v[8:11], v[162:165], v[202:205], v[8:11]
	v_mfma_f32_16x16x32_bf16 v[8:11], v[166:169], v[206:209], v[8:11]
	v_mfma_f32_16x16x32_bf16 v[12:15], v[154:157], v[202:205], v[12:15]
	v_mfma_f32_16x16x32_bf16 v[12:15], v[158:161], v[206:209], v[12:15]
	v_mfma_f32_16x16x32_bf16 v[16:19], v[146:149], v[202:205], v[16:19]
	v_mfma_f32_16x16x32_bf16 v[16:19], v[150:153], v[206:209], v[16:19]
	s_setprio 0
	s_barrier
	s_add_u32 s42, s42, 0x100
	s_addc_u32 s43, s43, 0
	s_add_u32 s68, s68, 0x100
	s_addc_u32 s69, s69, 0
	s_cmp_ge_i32 s70, s46
	s_mov_b32 s18, s70
	s_cbranch_scc0 .LBB0_1876

.LBB0_2329:
	s_add_i32 s43, s12, 2
	v_add_u32_e32 v156, s83, v142
	v_add_u32_e32 v172, s44, v142
	s_add_u32 s10, s8, 0x100
	ds_read_b128 v[144:147], v156
	ds_read_b128 v[148:151], v156 offset:1024
	ds_read_b128 v[152:155], v156 offset:2048
	ds_read_b128 v[156:159], v156 offset:3072
	ds_read_b128 v[160:163], v172
	ds_read_b128 v[164:167], v172 offset:1024
	ds_read_b128 v[168:171], v172 offset:2048
	ds_read_b128 v[172:175], v172 offset:3072
	s_addc_u32 s11, s9, 0
	s_cmp_lg_u32 s42, s12
	s_cselect_b32 s46, s10, 0
	s_cselect_b32 s47, s11, 0
	s_add_u32 s12, s6, s46
	s_addc_u32 s13, s7, s47
	s_add_u32 s46, s4, s46
	s_addc_u32 s47, s5, s47
	v_lshl_add_u64 v[208:209], v[138:139], 0, s[8:9]
	s_add_i32 m0, s22, 0xc000
	ds_read_b128 v[176:179], v143
	ds_read_b128 v[180:183], v143 offset:1024
	ds_read_b128 v[184:187], v143 offset:2048
	ds_read_b128 v[188:191], v143 offset:3072
	ds_read_b128 v[192:195], v143 offset:4096
	ds_read_b128 v[196:199], v143 offset:5120
	ds_read_b128 v[200:203], v143 offset:6144
	ds_read_b128 v[204:207], v143 offset:7168
	global_load_lds_dwordx4 v[208:209], off
	v_lshl_add_u64 v[208:209], v[140:141], 0, s[8:9]
	s_add_i32 m0, s22, 0xe000
	s_nop 0
	global_load_lds_dwordx4 v[208:209], off
	s_waitcnt vmcnt(8)
	s_waitcnt lgkmcnt(0)
	s_barrier
	s_setprio 1
	s_waitcnt lgkmcnt(0)
	v_mfma_f32_16x16x32_bf16 v[124:127], v[144:147], v[176:179], v[124:127]
	v_mfma_f32_16x16x32_bf16 v[124:127], v[148:151], v[180:183], v[124:127]
	v_mfma_f32_16x16x32_bf16 v[128:131], v[152:155], v[176:179], v[128:131]
	v_mfma_f32_16x16x32_bf16 v[128:131], v[156:159], v[180:183], v[128:131]
	v_mfma_f32_16x16x32_bf16 v[120:123], v[160:163], v[176:179], v[120:123]
	v_mfma_f32_16x16x32_bf16 v[120:123], v[164:167], v[180:183], v[120:123]
	v_mfma_f32_16x16x32_bf16 v[116:119], v[168:171], v[176:179], v[116:119]
	v_mfma_f32_16x16x32_bf16 v[116:119], v[172:175], v[180:183], v[116:119]
	v_mfma_f32_16x16x32_bf16 v[100:103], v[168:171], v[184:187], v[100:103]
	v_mfma_f32_16x16x32_bf16 v[100:103], v[172:175], v[188:191], v[100:103]
	v_mfma_f32_16x16x32_bf16 v[104:107], v[160:163], v[184:187], v[104:107]
	v_mfma_f32_16x16x32_bf16 v[104:107], v[164:167], v[188:191], v[104:107]
	v_mfma_f32_16x16x32_bf16 v[108:111], v[152:155], v[184:187], v[108:111]
	v_mfma_f32_16x16x32_bf16 v[108:111], v[156:159], v[188:191], v[108:111]
	v_mfma_f32_16x16x32_bf16 v[112:115], v[144:147], v[184:187], v[112:115]
	v_mfma_f32_16x16x32_bf16 v[112:115], v[148:151], v[188:191], v[112:115]
	s_setprio 0
	s_setprio 1
	v_mfma_f32_16x16x32_bf16 v[96:99], v[144:147], v[192:195], v[96:99]
	v_mfma_f32_16x16x32_bf16 v[96:99], v[148:151], v[196:199], v[96:99]
	v_mfma_f32_16x16x32_bf16 v[92:95], v[152:155], v[192:195], v[92:95]
	v_mfma_f32_16x16x32_bf16 v[92:95], v[156:159], v[196:199], v[92:95]
	v_mfma_f32_16x16x32_bf16 v[88:91], v[160:163], v[192:195], v[88:91]
	v_mfma_f32_16x16x32_bf16 v[88:91], v[164:167], v[196:199], v[88:91]
	v_mfma_f32_16x16x32_bf16 v[84:87], v[168:171], v[192:195], v[84:87]
	v_mfma_f32_16x16x32_bf16 v[84:87], v[172:175], v[196:199], v[84:87]
	v_mfma_f32_16x16x32_bf16 v[68:71], v[168:171], v[200:203], v[68:71]
	v_mfma_f32_16x16x32_bf16 v[68:71], v[172:175], v[204:207], v[68:71]
	v_mfma_f32_16x16x32_bf16 v[72:75], v[160:163], v[200:203], v[72:75]
	v_mfma_f32_16x16x32_bf16 v[72:75], v[164:167], v[204:207], v[72:75]
	v_mfma_f32_16x16x32_bf16 v[76:79], v[152:155], v[200:203], v[76:79]
	v_mfma_f32_16x16x32_bf16 v[76:79], v[156:159], v[204:207], v[76:79]
	v_mfma_f32_16x16x32_bf16 v[80:83], v[144:147], v[200:203], v[80:83]
	v_mfma_f32_16x16x32_bf16 v[80:83], v[148:151], v[204:207], v[80:83]
	s_setprio 0
	s_barrier
	s_mov_b32 m0, s18
	v_lshl_add_u64 v[208:209], s[46:47], 0, v[2:3]
	s_add_u32 s8, s46, s2
	ds_read_b128 v[176:179], v143 offset:16384
	ds_read_b128 v[180:183], v143 offset:17408
	ds_read_b128 v[184:187], v143 offset:18432
	ds_read_b128 v[188:191], v143 offset:19456
	ds_read_b128 v[192:195], v143 offset:20480
	ds_read_b128 v[196:199], v143 offset:21504
	ds_read_b128 v[200:203], v143 offset:22528
	ds_read_b128 v[204:207], v143 offset:23552
	global_load_lds_dwordx4 v[208:209], off
	v_lshl_add_u64 v[210:211], s[46:47], 0, v[136:137]
	s_mov_b32 m0, s19
	s_addc_u32 s9, s47, s3
	global_load_lds_dwordx4 v[210:211], off
	v_lshl_add_u64 v[216:217], s[8:9], 0, v[2:3]
	s_mov_b32 m0, s20
	v_lshl_add_u64 v[218:219], s[8:9], 0, v[136:137]
	global_load_lds_dwordx4 v[216:217], off
	s_mov_b32 m0, s21
	v_lshl_add_u64 v[220:221], s[12:13], 0, v[132:133]
	global_load_lds_dwordx4 v[218:219], off
	s_mov_b32 m0, s22
	v_lshl_add_u64 v[222:223], s[12:13], 0, v[134:135]
	global_load_lds_dwordx4 v[220:221], off
	s_mov_b32 m0, s23
	s_nop 0
	global_load_lds_dwordx4 v[222:223], off
	s_waitcnt vmcnt(8)
	s_waitcnt lgkmcnt(0)
	s_barrier
	s_setprio 1
	s_waitcnt lgkmcnt(0)
	v_mfma_f32_16x16x32_bf16 v[64:67], v[144:147], v[176:179], v[64:67]
	v_mfma_f32_16x16x32_bf16 v[64:67], v[148:151], v[180:183], v[64:67]
	v_mfma_f32_16x16x32_bf16 v[60:63], v[152:155], v[176:179], v[60:63]
	v_mfma_f32_16x16x32_bf16 v[60:63], v[156:159], v[180:183], v[60:63]
	v_mfma_f32_16x16x32_bf16 v[56:59], v[160:163], v[176:179], v[56:59]
	v_mfma_f32_16x16x32_bf16 v[56:59], v[164:167], v[180:183], v[56:59]
	v_mfma_f32_16x16x32_bf16 v[52:55], v[168:171], v[176:179], v[52:55]
	v_mfma_f32_16x16x32_bf16 v[52:55], v[172:175], v[180:183], v[52:55]
	v_mfma_f32_16x16x32_bf16 v[36:39], v[168:171], v[184:187], v[36:39]
	v_mfma_f32_16x16x32_bf16 v[36:39], v[172:175], v[188:191], v[36:39]
	v_mfma_f32_16x16x32_bf16 v[40:43], v[160:163], v[184:187], v[40:43]
	v_mfma_f32_16x16x32_bf16 v[40:43], v[164:167], v[188:191], v[40:43]
	v_mfma_f32_16x16x32_bf16 v[44:47], v[152:155], v[184:187], v[44:47]
	v_mfma_f32_16x16x32_bf16 v[44:47], v[156:159], v[188:191], v[44:47]
	v_mfma_f32_16x16x32_bf16 v[48:51], v[144:147], v[184:187], v[48:51]
	v_mfma_f32_16x16x32_bf16 v[48:51], v[148:151], v[188:191], v[48:51]
	s_setprio 0
	s_setprio 1
	v_mfma_f32_16x16x32_bf16 v[32:35], v[144:147], v[192:195], v[32:35]
	v_mfma_f32_16x16x32_bf16 v[32:35], v[148:151], v[196:199], v[32:35]
	v_mfma_f32_16x16x32_bf16 v[28:31], v[152:155], v[192:195], v[28:31]
	v_mfma_f32_16x16x32_bf16 v[28:31], v[156:159], v[196:199], v[28:31]
	v_mfma_f32_16x16x32_bf16 v[24:27], v[160:163], v[192:195], v[24:27]
	v_mfma_f32_16x16x32_bf16 v[24:27], v[164:167], v[196:199], v[24:27]
	v_mfma_f32_16x16x32_bf16 v[20:23], v[168:171], v[192:195], v[20:23]
	v_mfma_f32_16x16x32_bf16 v[20:23], v[172:175], v[196:199], v[20:23]
	v_mfma_f32_16x16x32_bf16 v[4:7], v[168:171], v[200:203], v[4:7]
	v_mfma_f32_16x16x32_bf16 v[4:7], v[172:175], v[204:207], v[4:7]
	v_mfma_f32_16x16x32_bf16 v[8:11], v[160:163], v[200:203], v[8:11]
	v_mfma_f32_16x16x32_bf16 v[8:11], v[164:167], v[204:207], v[8:11]
	v_mfma_f32_16x16x32_bf16 v[12:15], v[152:155], v[200:203], v[12:15]
	v_mfma_f32_16x16x32_bf16 v[12:15], v[156:159], v[204:207], v[12:15]
	v_mfma_f32_16x16x32_bf16 v[16:19], v[144:147], v[200:203], v[16:19]
	v_mfma_f32_16x16x32_bf16 v[16:19], v[148:151], v[204:207], v[16:19]
	s_setprio 0
	s_barrier
	v_add_u32_e32 v156, s45, v142
	v_add_u32_e32 v172, s74, v142
	ds_read_b128 v[144:147], v156
	ds_read_b128 v[148:151], v156 offset:1024
	ds_read_b128 v[152:155], v156 offset:2048
	ds_read_b128 v[156:159], v156 offset:3072
	ds_read_b128 v[160:163], v172
	ds_read_b128 v[164:167], v172 offset:1024
	ds_read_b128 v[168:171], v172 offset:2048
	ds_read_b128 v[172:175], v172 offset:3072
	s_add_u32 s8, s12, s2
	s_addc_u32 s9, s13, s3
	s_mov_b32 m0, s24
	v_lshl_add_u64 v[224:225], s[8:9], 0, v[132:133]
	ds_read_b128 v[176:179], v143 offset:32768
	ds_read_b128 v[180:183], v143 offset:33792
	ds_read_b128 v[184:187], v143 offset:34816
	ds_read_b128 v[188:191], v143 offset:35840
	ds_read_b128 v[192:195], v143 offset:36864
	ds_read_b128 v[196:199], v143 offset:37888
	ds_read_b128 v[200:203], v143 offset:38912
	ds_read_b128 v[204:207], v143 offset:39936
	global_load_lds_dwordx4 v[224:225], off
	v_lshl_add_u64 v[224:225], s[8:9], 0, v[134:135]
	s_mov_b32 m0, s25
	s_nop 0
	global_load_lds_dwordx4 v[224:225], off
	s_waitcnt vmcnt(8)
	s_waitcnt lgkmcnt(0)
	s_barrier
	s_setprio 1
	s_waitcnt lgkmcnt(0)
	v_mfma_f32_16x16x32_bf16 v[124:127], v[144:147], v[176:179], v[124:127]
	v_mfma_f32_16x16x32_bf16 v[124:127], v[148:151], v[180:183], v[124:127]
	v_mfma_f32_16x16x32_bf16 v[128:131], v[152:155], v[176:179], v[128:131]
	v_mfma_f32_16x16x32_bf16 v[128:131], v[156:159], v[180:183], v[128:131]
	v_mfma_f32_16x16x32_bf16 v[120:123], v[160:163], v[176:179], v[120:123]
	v_mfma_f32_16x16x32_bf16 v[120:123], v[164:167], v[180:183], v[120:123]
	v_mfma_f32_16x16x32_bf16 v[116:119], v[168:171], v[176:179], v[116:119]
	v_mfma_f32_16x16x32_bf16 v[116:119], v[172:175], v[180:183], v[116:119]
	v_mfma_f32_16x16x32_bf16 v[100:103], v[168:171], v[184:187], v[100:103]
	v_mfma_f32_16x16x32_bf16 v[100:103], v[172:175], v[188:191], v[100:103]
	v_mfma_f32_16x16x32_bf16 v[104:107], v[160:163], v[184:187], v[104:107]
	v_mfma_f32_16x16x32_bf16 v[104:107], v[164:167], v[188:191], v[104:107]
	v_mfma_f32_16x16x32_bf16 v[108:111], v[152:155], v[184:187], v[108:111]
	v_mfma_f32_16x16x32_bf16 v[108:111], v[156:159], v[188:191], v[108:111]
	v_mfma_f32_16x16x32_bf16 v[112:115], v[144:147], v[184:187], v[112:115]
	v_mfma_f32_16x16x32_bf16 v[112:115], v[148:151], v[188:191], v[112:115]
	s_setprio 0
	s_setprio 1
	v_mfma_f32_16x16x32_bf16 v[96:99], v[144:147], v[192:195], v[96:99]
	v_mfma_f32_16x16x32_bf16 v[96:99], v[148:151], v[196:199], v[96:99]
	v_mfma_f32_16x16x32_bf16 v[92:95], v[152:155], v[192:195], v[92:95]
	v_mfma_f32_16x16x32_bf16 v[92:95], v[156:159], v[196:199], v[92:95]
	v_mfma_f32_16x16x32_bf16 v[88:91], v[160:163], v[192:195], v[88:91]
	v_mfma_f32_16x16x32_bf16 v[88:91], v[164:167], v[196:199], v[88:91]
	v_mfma_f32_16x16x32_bf16 v[84:87], v[168:171], v[192:195], v[84:87]
	v_mfma_f32_16x16x32_bf16 v[84:87], v[172:175], v[196:199], v[84:87]
	v_mfma_f32_16x16x32_bf16 v[68:71], v[168:171], v[200:203], v[68:71]
	v_mfma_f32_16x16x32_bf16 v[68:71], v[172:175], v[204:207], v[68:71]
	v_mfma_f32_16x16x32_bf16 v[72:75], v[160:163], v[200:203], v[72:75]
	v_mfma_f32_16x16x32_bf16 v[72:75], v[164:167], v[204:207], v[72:75]
	v_mfma_f32_16x16x32_bf16 v[76:79], v[152:155], v[200:203], v[76:79]
	v_mfma_f32_16x16x32_bf16 v[76:79], v[156:159], v[204:207], v[76:79]
	v_mfma_f32_16x16x32_bf16 v[80:83], v[144:147], v[200:203], v[80:83]
	v_mfma_f32_16x16x32_bf16 v[80:83], v[148:151], v[204:207], v[80:83]
	s_setprio 0
	s_barrier
	s_mov_b32 m0, s26
	v_lshl_add_u64 v[208:209], v[208:209], 0, s[64:65]
	ds_read_b128 v[176:179], v143 offset:49152
	ds_read_b128 v[180:183], v143 offset:50176
	ds_read_b128 v[184:187], v143 offset:51200
	ds_read_b128 v[188:191], v143 offset:52224
	ds_read_b128 v[192:195], v143 offset:53248
	ds_read_b128 v[196:199], v143 offset:54272
	ds_read_b128 v[200:203], v143 offset:55296
	ds_read_b128 v[204:207], v143 offset:56320
	global_load_lds_dwordx4 v[208:209], off
	v_lshl_add_u64 v[208:209], v[210:211], 0, s[64:65]
	s_mov_b32 m0, s27
	s_nop 0
	global_load_lds_dwordx4 v[208:209], off
	v_lshl_add_u64 v[208:209], v[216:217], 0, s[64:65]
	s_mov_b32 m0, s37
	s_nop 0
	global_load_lds_dwordx4 v[208:209], off
	v_lshl_add_u64 v[208:209], v[218:219], 0, s[64:65]
	s_mov_b32 m0, s40
	s_nop 0
	global_load_lds_dwordx4 v[208:209], off
	v_lshl_add_u64 v[208:209], v[220:221], 0, s[64:65]
	s_mov_b32 m0, s34
	s_nop 0
	global_load_lds_dwordx4 v[208:209], off
	v_lshl_add_u64 v[208:209], v[222:223], 0, s[64:65]
	s_mov_b32 m0, s35
	s_nop 0
	global_load_lds_dwordx4 v[208:209], off
	s_waitcnt vmcnt(8)
	s_waitcnt lgkmcnt(0)
	s_barrier
	s_setprio 1
	s_waitcnt lgkmcnt(0)
	v_mfma_f32_16x16x32_bf16 v[64:67], v[144:147], v[176:179], v[64:67]
	v_mfma_f32_16x16x32_bf16 v[64:67], v[148:151], v[180:183], v[64:67]
	v_mfma_f32_16x16x32_bf16 v[60:63], v[152:155], v[176:179], v[60:63]
	v_mfma_f32_16x16x32_bf16 v[60:63], v[156:159], v[180:183], v[60:63]
	v_mfma_f32_16x16x32_bf16 v[56:59], v[160:163], v[176:179], v[56:59]
	v_mfma_f32_16x16x32_bf16 v[56:59], v[164:167], v[180:183], v[56:59]
	v_mfma_f32_16x16x32_bf16 v[52:55], v[168:171], v[176:179], v[52:55]
	v_mfma_f32_16x16x32_bf16 v[52:55], v[172:175], v[180:183], v[52:55]
	v_mfma_f32_16x16x32_bf16 v[36:39], v[168:171], v[184:187], v[36:39]
	v_mfma_f32_16x16x32_bf16 v[36:39], v[172:175], v[188:191], v[36:39]
	v_mfma_f32_16x16x32_bf16 v[40:43], v[160:163], v[184:187], v[40:43]
	v_mfma_f32_16x16x32_bf16 v[40:43], v[164:167], v[188:191], v[40:43]
	v_mfma_f32_16x16x32_bf16 v[44:47], v[152:155], v[184:187], v[44:47]
	v_mfma_f32_16x16x32_bf16 v[44:47], v[156:159], v[188:191], v[44:47]
	v_mfma_f32_16x16x32_bf16 v[48:51], v[144:147], v[184:187], v[48:51]
	v_mfma_f32_16x16x32_bf16 v[48:51], v[148:151], v[188:191], v[48:51]
	s_setprio 0
	s_setprio 1
	v_mfma_f32_16x16x32_bf16 v[32:35], v[144:147], v[192:195], v[32:35]
	v_mfma_f32_16x16x32_bf16 v[32:35], v[148:151], v[196:199], v[32:35]
	v_mfma_f32_16x16x32_bf16 v[28:31], v[152:155], v[192:195], v[28:31]
	v_mfma_f32_16x16x32_bf16 v[28:31], v[156:159], v[196:199], v[28:31]
	v_mfma_f32_16x16x32_bf16 v[24:27], v[160:163], v[192:195], v[24:27]
	v_mfma_f32_16x16x32_bf16 v[24:27], v[164:167], v[196:199], v[24:27]
	v_mfma_f32_16x16x32_bf16 v[20:23], v[168:171], v[192:195], v[20:23]
	v_mfma_f32_16x16x32_bf16 v[20:23], v[172:175], v[196:199], v[20:23]
	v_mfma_f32_16x16x32_bf16 v[4:7], v[168:171], v[200:203], v[4:7]
	v_mfma_f32_16x16x32_bf16 v[4:7], v[172:175], v[204:207], v[4:7]
	v_mfma_f32_16x16x32_bf16 v[8:11], v[160:163], v[200:203], v[8:11]
	v_mfma_f32_16x16x32_bf16 v[8:11], v[164:167], v[204:207], v[8:11]
	v_mfma_f32_16x16x32_bf16 v[12:15], v[152:155], v[200:203], v[12:15]
	v_mfma_f32_16x16x32_bf16 v[12:15], v[156:159], v[204:207], v[12:15]
	v_mfma_f32_16x16x32_bf16 v[16:19], v[144:147], v[200:203], v[16:19]
	v_mfma_f32_16x16x32_bf16 v[16:19], v[148:151], v[204:207], v[16:19]
	s_setprio 0
	s_barrier
	s_cmp_ge_i32 s43, s41
	s_mov_b64 s[8:9], s[10:11]
	s_mov_b32 s12, s43
	s_cbranch_scc0 .LBB0_2329

.LBB0_2896:
	v_add_u32_e32 v148, s18, v126
	v_add_u32_e32 v172, s19, v126
	s_add_u32 s12, s46, s8
	ds_read_b128 v[128:131], v148
	ds_read_b128 v[132:135], v148 offset:1024
	ds_read_b128 v[140:143], v148 offset:2048
	ds_read_b128 v[148:151], v148 offset:3072
	ds_read_b128 v[160:163], v172
	ds_read_b128 v[164:167], v172 offset:1024
	ds_read_b128 v[168:171], v172 offset:2048
	ds_read_b128 v[172:175], v172 offset:3072
	s_addc_u32 s13, s47, s9
	s_add_u32 s12, s12, 0x34400100
	s_addc_u32 s13, s13, 0
	s_add_u32 s16, s48, s8
	s_addc_u32 s51, s49, s9
	s_cmpk_eq_i32 s8, 0xf00
	s_cselect_b32 s15, s11, s13
	s_cselect_b32 s14, s10, s12
	s_cselect_b32 s13, s3, s51
	s_cselect_b32 s12, s2, s16
	v_lshl_add_u64 v[208:209], v[122:123], 0, s[8:9]
	s_add_i32 m0, s27, 0xc000
	ds_read_b128 v[176:179], v127
	ds_read_b128 v[180:183], v127 offset:1024
	ds_read_b128 v[184:187], v127 offset:2048
	ds_read_b128 v[188:191], v127 offset:3072
	ds_read_b128 v[192:195], v127 offset:4096
	ds_read_b128 v[196:199], v127 offset:5120
	ds_read_b128 v[200:203], v127 offset:6144
	ds_read_b128 v[204:207], v127 offset:7168
	global_load_lds_dwordx4 v[208:209], off
	v_lshl_add_u64 v[208:209], v[124:125], 0, s[8:9]
	s_add_i32 m0, s27, 0xe000
	s_nop 0
	global_load_lds_dwordx4 v[208:209], off
	s_waitcnt vmcnt(8)
	s_waitcnt lgkmcnt(0)
	s_barrier
	s_setprio 1
	s_waitcnt lgkmcnt(0)
	v_mfma_f32_16x16x32_bf16 v[156:159], v[128:131], v[176:179], v[156:159]
	v_mfma_f32_16x16x32_bf16 v[156:159], v[132:135], v[180:183], v[156:159]
	v_mfma_f32_16x16x32_bf16 v[152:155], v[140:143], v[176:179], v[152:155]
	v_mfma_f32_16x16x32_bf16 v[152:155], v[148:151], v[180:183], v[152:155]
	v_mfma_f32_16x16x32_bf16 v[144:147], v[160:163], v[176:179], v[144:147]
	v_mfma_f32_16x16x32_bf16 v[144:147], v[164:167], v[180:183], v[144:147]
	v_mfma_f32_16x16x32_bf16 v[136:139], v[168:171], v[176:179], v[136:139]
	v_mfma_f32_16x16x32_bf16 v[136:139], v[172:175], v[180:183], v[136:139]
	v_mfma_f32_16x16x32_bf16 v[100:103], v[168:171], v[184:187], v[100:103]
	v_mfma_f32_16x16x32_bf16 v[100:103], v[172:175], v[188:191], v[100:103]
	v_mfma_f32_16x16x32_bf16 v[104:107], v[160:163], v[184:187], v[104:107]
	v_mfma_f32_16x16x32_bf16 v[104:107], v[164:167], v[188:191], v[104:107]
	v_mfma_f32_16x16x32_bf16 v[108:111], v[140:143], v[184:187], v[108:111]
	v_mfma_f32_16x16x32_bf16 v[108:111], v[148:151], v[188:191], v[108:111]
	v_mfma_f32_16x16x32_bf16 v[112:115], v[128:131], v[184:187], v[112:115]
	v_mfma_f32_16x16x32_bf16 v[112:115], v[132:135], v[188:191], v[112:115]
	s_setprio 0
	s_setprio 1
	v_mfma_f32_16x16x32_bf16 v[96:99], v[128:131], v[192:195], v[96:99]
	v_mfma_f32_16x16x32_bf16 v[96:99], v[132:135], v[196:199], v[96:99]
	v_mfma_f32_16x16x32_bf16 v[92:95], v[140:143], v[192:195], v[92:95]
	v_mfma_f32_16x16x32_bf16 v[92:95], v[148:151], v[196:199], v[92:95]
	v_mfma_f32_16x16x32_bf16 v[88:91], v[160:163], v[192:195], v[88:91]
	v_mfma_f32_16x16x32_bf16 v[88:91], v[164:167], v[196:199], v[88:91]
	v_mfma_f32_16x16x32_bf16 v[84:87], v[168:171], v[192:195], v[84:87]
	v_mfma_f32_16x16x32_bf16 v[84:87], v[172:175], v[196:199], v[84:87]
	v_mfma_f32_16x16x32_bf16 v[68:71], v[168:171], v[200:203], v[68:71]
	v_mfma_f32_16x16x32_bf16 v[68:71], v[172:175], v[204:207], v[68:71]
	v_mfma_f32_16x16x32_bf16 v[72:75], v[160:163], v[200:203], v[72:75]
	v_mfma_f32_16x16x32_bf16 v[72:75], v[164:167], v[204:207], v[72:75]
	v_mfma_f32_16x16x32_bf16 v[76:79], v[140:143], v[200:203], v[76:79]
	v_mfma_f32_16x16x32_bf16 v[76:79], v[148:151], v[204:207], v[76:79]
	v_mfma_f32_16x16x32_bf16 v[80:83], v[128:131], v[200:203], v[80:83]
	v_mfma_f32_16x16x32_bf16 v[80:83], v[132:135], v[204:207], v[80:83]
	s_setprio 0
	s_barrier
	s_mov_b32 m0, s23
	v_lshl_add_u64 v[208:209], s[12:13], 0, v[2:3]
	s_add_u32 s52, s12, 0x80000
	ds_read_b128 v[176:179], v127 offset:16384
	ds_read_b128 v[180:183], v127 offset:17408
	ds_read_b128 v[184:187], v127 offset:18432
	ds_read_b128 v[188:191], v127 offset:19456
	ds_read_b128 v[192:195], v127 offset:20480
	ds_read_b128 v[196:199], v127 offset:21504
	ds_read_b128 v[200:203], v127 offset:22528
	ds_read_b128 v[204:207], v127 offset:23552
	global_load_lds_dwordx4 v[208:209], off
	v_lshl_add_u64 v[210:211], s[12:13], 0, v[120:121]
	s_mov_b32 m0, s24
	s_addc_u32 s53, s13, 0
	global_load_lds_dwordx4 v[210:211], off
	v_lshl_add_u64 v[216:217], s[52:53], 0, v[2:3]
	s_mov_b32 m0, s25
	v_lshl_add_u64 v[218:219], s[14:15], 0, v[118:119]
	global_load_lds_dwordx4 v[216:217], off
	v_lshl_add_u64 v[216:217], s[52:53], 0, v[120:121]
	s_mov_b32 m0, s26
	s_nop 0
	global_load_lds_dwordx4 v[216:217], off
	v_lshl_add_u64 v[216:217], s[14:15], 0, v[116:117]
	s_mov_b32 m0, s27
	s_nop 0
	global_load_lds_dwordx4 v[216:217], off
	s_mov_b32 m0, s35
	s_nop 0
	global_load_lds_dwordx4 v[218:219], off
	s_waitcnt vmcnt(8)
	s_waitcnt lgkmcnt(0)
	s_barrier
	s_setprio 1
	s_waitcnt lgkmcnt(0)
	v_mfma_f32_16x16x32_bf16 v[64:67], v[128:131], v[176:179], v[64:67]
	v_mfma_f32_16x16x32_bf16 v[64:67], v[132:135], v[180:183], v[64:67]
	v_mfma_f32_16x16x32_bf16 v[60:63], v[140:143], v[176:179], v[60:63]
	v_mfma_f32_16x16x32_bf16 v[60:63], v[148:151], v[180:183], v[60:63]
	v_mfma_f32_16x16x32_bf16 v[56:59], v[160:163], v[176:179], v[56:59]
	v_mfma_f32_16x16x32_bf16 v[56:59], v[164:167], v[180:183], v[56:59]
	v_mfma_f32_16x16x32_bf16 v[52:55], v[168:171], v[176:179], v[52:55]
	v_mfma_f32_16x16x32_bf16 v[52:55], v[172:175], v[180:183], v[52:55]
	v_mfma_f32_16x16x32_bf16 v[36:39], v[168:171], v[184:187], v[36:39]
	v_mfma_f32_16x16x32_bf16 v[36:39], v[172:175], v[188:191], v[36:39]
	v_mfma_f32_16x16x32_bf16 v[40:43], v[160:163], v[184:187], v[40:43]
	v_mfma_f32_16x16x32_bf16 v[40:43], v[164:167], v[188:191], v[40:43]
	v_mfma_f32_16x16x32_bf16 v[44:47], v[140:143], v[184:187], v[44:47]
	v_mfma_f32_16x16x32_bf16 v[44:47], v[148:151], v[188:191], v[44:47]
	v_mfma_f32_16x16x32_bf16 v[48:51], v[128:131], v[184:187], v[48:51]
	v_mfma_f32_16x16x32_bf16 v[48:51], v[132:135], v[188:191], v[48:51]
	s_setprio 0
	s_setprio 1
	v_mfma_f32_16x16x32_bf16 v[32:35], v[128:131], v[192:195], v[32:35]
	v_mfma_f32_16x16x32_bf16 v[32:35], v[132:135], v[196:199], v[32:35]
	v_mfma_f32_16x16x32_bf16 v[28:31], v[140:143], v[192:195], v[28:31]
	v_mfma_f32_16x16x32_bf16 v[28:31], v[148:151], v[196:199], v[28:31]
	v_mfma_f32_16x16x32_bf16 v[24:27], v[160:163], v[192:195], v[24:27]
	v_mfma_f32_16x16x32_bf16 v[24:27], v[164:167], v[196:199], v[24:27]
	v_mfma_f32_16x16x32_bf16 v[20:23], v[168:171], v[192:195], v[20:23]
	v_mfma_f32_16x16x32_bf16 v[20:23], v[172:175], v[196:199], v[20:23]
	v_mfma_f32_16x16x32_bf16 v[4:7], v[168:171], v[200:203], v[4:7]
	v_mfma_f32_16x16x32_bf16 v[4:7], v[172:175], v[204:207], v[4:7]
	v_mfma_f32_16x16x32_bf16 v[8:11], v[160:163], v[200:203], v[8:11]
	v_mfma_f32_16x16x32_bf16 v[8:11], v[164:167], v[204:207], v[8:11]
	v_mfma_f32_16x16x32_bf16 v[12:15], v[140:143], v[200:203], v[12:15]
	v_mfma_f32_16x16x32_bf16 v[12:15], v[148:151], v[204:207], v[12:15]
	v_mfma_f32_16x16x32_bf16 v[16:19], v[128:131], v[200:203], v[16:19]
	v_mfma_f32_16x16x32_bf16 v[16:19], v[132:135], v[204:207], v[16:19]
	s_setprio 0
	s_barrier
	v_add_u32_e32 v148, s20, v126
	v_add_u32_e32 v172, s21, v126
	ds_read_b128 v[128:131], v148
	ds_read_b128 v[132:135], v148 offset:1024
	ds_read_b128 v[140:143], v148 offset:2048
	ds_read_b128 v[148:151], v148 offset:3072
	ds_read_b128 v[160:163], v172
	ds_read_b128 v[164:167], v172 offset:1024
	ds_read_b128 v[168:171], v172 offset:2048
	ds_read_b128 v[172:175], v172 offset:3072
	s_add_u32 s14, s14, 0x80000
	s_addc_u32 s15, s15, 0
	s_mov_b32 m0, s37
	v_lshl_add_u64 v[220:221], s[14:15], 0, v[116:117]
	ds_read_b128 v[176:179], v127 offset:32768
	ds_read_b128 v[180:183], v127 offset:33792
	ds_read_b128 v[184:187], v127 offset:34816
	ds_read_b128 v[188:191], v127 offset:35840
	ds_read_b128 v[192:195], v127 offset:36864
	ds_read_b128 v[196:199], v127 offset:37888
	ds_read_b128 v[200:203], v127 offset:38912
	ds_read_b128 v[204:207], v127 offset:39936
	global_load_lds_dwordx4 v[220:221], off
	v_lshl_add_u64 v[220:221], s[14:15], 0, v[118:119]
	s_mov_b32 m0, s38
	s_nop 0
	global_load_lds_dwordx4 v[220:221], off
	s_waitcnt vmcnt(8)
	s_waitcnt lgkmcnt(0)
	s_barrier
	s_setprio 1
	s_waitcnt lgkmcnt(0)
	v_mfma_f32_16x16x32_bf16 v[156:159], v[128:131], v[176:179], v[156:159]
	v_mfma_f32_16x16x32_bf16 v[156:159], v[132:135], v[180:183], v[156:159]
	v_mfma_f32_16x16x32_bf16 v[152:155], v[140:143], v[176:179], v[152:155]
	v_mfma_f32_16x16x32_bf16 v[152:155], v[148:151], v[180:183], v[152:155]
	v_mfma_f32_16x16x32_bf16 v[144:147], v[160:163], v[176:179], v[144:147]
	v_mfma_f32_16x16x32_bf16 v[144:147], v[164:167], v[180:183], v[144:147]
	v_mfma_f32_16x16x32_bf16 v[136:139], v[168:171], v[176:179], v[136:139]
	v_mfma_f32_16x16x32_bf16 v[136:139], v[172:175], v[180:183], v[136:139]
	v_mfma_f32_16x16x32_bf16 v[100:103], v[168:171], v[184:187], v[100:103]
	v_mfma_f32_16x16x32_bf16 v[100:103], v[172:175], v[188:191], v[100:103]
	v_mfma_f32_16x16x32_bf16 v[104:107], v[160:163], v[184:187], v[104:107]
	v_mfma_f32_16x16x32_bf16 v[104:107], v[164:167], v[188:191], v[104:107]
	v_mfma_f32_16x16x32_bf16 v[108:111], v[140:143], v[184:187], v[108:111]
	v_mfma_f32_16x16x32_bf16 v[108:111], v[148:151], v[188:191], v[108:111]
	v_mfma_f32_16x16x32_bf16 v[112:115], v[128:131], v[184:187], v[112:115]
	v_mfma_f32_16x16x32_bf16 v[112:115], v[132:135], v[188:191], v[112:115]
	s_setprio 0
	s_setprio 1
	v_mfma_f32_16x16x32_bf16 v[96:99], v[128:131], v[192:195], v[96:99]
	v_mfma_f32_16x16x32_bf16 v[96:99], v[132:135], v[196:199], v[96:99]
	v_mfma_f32_16x16x32_bf16 v[92:95], v[140:143], v[192:195], v[92:95]
	v_mfma_f32_16x16x32_bf16 v[92:95], v[148:151], v[196:199], v[92:95]
	v_mfma_f32_16x16x32_bf16 v[88:91], v[160:163], v[192:195], v[88:91]
	v_mfma_f32_16x16x32_bf16 v[88:91], v[164:167], v[196:199], v[88:91]
	v_mfma_f32_16x16x32_bf16 v[84:87], v[168:171], v[192:195], v[84:87]
	v_mfma_f32_16x16x32_bf16 v[84:87], v[172:175], v[196:199], v[84:87]
	v_mfma_f32_16x16x32_bf16 v[68:71], v[168:171], v[200:203], v[68:71]
	v_mfma_f32_16x16x32_bf16 v[68:71], v[172:175], v[204:207], v[68:71]
	v_mfma_f32_16x16x32_bf16 v[72:75], v[160:163], v[200:203], v[72:75]
	v_mfma_f32_16x16x32_bf16 v[72:75], v[164:167], v[204:207], v[72:75]
	v_mfma_f32_16x16x32_bf16 v[76:79], v[140:143], v[200:203], v[76:79]
	v_mfma_f32_16x16x32_bf16 v[76:79], v[148:151], v[204:207], v[76:79]
	v_mfma_f32_16x16x32_bf16 v[80:83], v[128:131], v[200:203], v[80:83]
	v_mfma_f32_16x16x32_bf16 v[80:83], v[132:135], v[204:207], v[80:83]
	s_setprio 0
	s_barrier
	s_mov_b32 m0, s40
	v_lshl_add_u64 v[208:209], v[208:209], 0, s[64:65]
	s_add_u32 s12, s12, 0x80080
	ds_read_b128 v[176:179], v127 offset:49152
	ds_read_b128 v[180:183], v127 offset:50176
	ds_read_b128 v[184:187], v127 offset:51200
	ds_read_b128 v[188:191], v127 offset:52224
	ds_read_b128 v[192:195], v127 offset:53248
	ds_read_b128 v[196:199], v127 offset:54272
	ds_read_b128 v[200:203], v127 offset:55296
	ds_read_b128 v[204:207], v127 offset:56320
	global_load_lds_dwordx4 v[208:209], off
	v_lshl_add_u64 v[208:209], v[210:211], 0, s[64:65]
	s_mov_b32 m0, s41
	s_addc_u32 s13, s13, 0
	global_load_lds_dwordx4 v[208:209], off
	v_lshl_add_u64 v[208:209], s[12:13], 0, v[2:3]
	s_mov_b32 m0, s44
	s_nop 0
	global_load_lds_dwordx4 v[208:209], off
	v_lshl_add_u64 v[208:209], s[12:13], 0, v[120:121]
	s_mov_b32 m0, s45
	s_nop 0
	global_load_lds_dwordx4 v[208:209], off
	v_lshl_add_u64 v[208:209], v[216:217], 0, s[64:65]
	s_mov_b32 m0, s42
	s_nop 0
	global_load_lds_dwordx4 v[208:209], off
	v_lshl_add_u64 v[208:209], v[218:219], 0, s[64:65]
	s_mov_b32 m0, s43
	s_nop 0
	global_load_lds_dwordx4 v[208:209], off
	s_waitcnt vmcnt(8)
	s_waitcnt lgkmcnt(0)
	s_barrier
	s_setprio 1
	s_waitcnt lgkmcnt(0)
	v_mfma_f32_16x16x32_bf16 v[64:67], v[128:131], v[176:179], v[64:67]
	v_mfma_f32_16x16x32_bf16 v[64:67], v[132:135], v[180:183], v[64:67]
	v_mfma_f32_16x16x32_bf16 v[60:63], v[140:143], v[176:179], v[60:63]
	v_mfma_f32_16x16x32_bf16 v[60:63], v[148:151], v[180:183], v[60:63]
	v_mfma_f32_16x16x32_bf16 v[56:59], v[160:163], v[176:179], v[56:59]
	v_mfma_f32_16x16x32_bf16 v[56:59], v[164:167], v[180:183], v[56:59]
	v_mfma_f32_16x16x32_bf16 v[52:55], v[168:171], v[176:179], v[52:55]
	v_mfma_f32_16x16x32_bf16 v[52:55], v[172:175], v[180:183], v[52:55]
	v_mfma_f32_16x16x32_bf16 v[36:39], v[168:171], v[184:187], v[36:39]
	v_mfma_f32_16x16x32_bf16 v[36:39], v[172:175], v[188:191], v[36:39]
	v_mfma_f32_16x16x32_bf16 v[40:43], v[160:163], v[184:187], v[40:43]
	v_mfma_f32_16x16x32_bf16 v[40:43], v[164:167], v[188:191], v[40:43]
	v_mfma_f32_16x16x32_bf16 v[44:47], v[140:143], v[184:187], v[44:47]
	v_mfma_f32_16x16x32_bf16 v[44:47], v[148:151], v[188:191], v[44:47]
	v_mfma_f32_16x16x32_bf16 v[48:51], v[128:131], v[184:187], v[48:51]
	v_mfma_f32_16x16x32_bf16 v[48:51], v[132:135], v[188:191], v[48:51]
	s_setprio 0
	s_setprio 1
	v_mfma_f32_16x16x32_bf16 v[32:35], v[128:131], v[192:195], v[32:35]
	v_mfma_f32_16x16x32_bf16 v[32:35], v[132:135], v[196:199], v[32:35]
	v_mfma_f32_16x16x32_bf16 v[28:31], v[140:143], v[192:195], v[28:31]
	v_mfma_f32_16x16x32_bf16 v[28:31], v[148:151], v[196:199], v[28:31]
	v_mfma_f32_16x16x32_bf16 v[24:27], v[160:163], v[192:195], v[24:27]
	v_mfma_f32_16x16x32_bf16 v[24:27], v[164:167], v[196:199], v[24:27]
	v_mfma_f32_16x16x32_bf16 v[20:23], v[168:171], v[192:195], v[20:23]
	v_mfma_f32_16x16x32_bf16 v[20:23], v[172:175], v[196:199], v[20:23]
	v_mfma_f32_16x16x32_bf16 v[4:7], v[168:171], v[200:203], v[4:7]
	v_mfma_f32_16x16x32_bf16 v[4:7], v[172:175], v[204:207], v[4:7]
	v_mfma_f32_16x16x32_bf16 v[8:11], v[160:163], v[200:203], v[8:11]
	v_mfma_f32_16x16x32_bf16 v[8:11], v[164:167], v[204:207], v[8:11]
	v_mfma_f32_16x16x32_bf16 v[12:15], v[140:143], v[200:203], v[12:15]
	v_mfma_f32_16x16x32_bf16 v[12:15], v[148:151], v[204:207], v[12:15]
	v_mfma_f32_16x16x32_bf16 v[16:19], v[128:131], v[200:203], v[16:19]
	v_mfma_f32_16x16x32_bf16 v[16:19], v[132:135], v[204:207], v[16:19]
	s_setprio 0
	s_barrier
	s_add_i32 s50, s50, 2
	s_add_u32 s8, s8, 0x100
	s_addc_u32 s9, s9, 0
	s_cmp_gt_u32 s50, 29
	s_cbranch_scc0 .LBB0_2896
	s_cmpk_lt_u32 s22, 0x100
	s_cbranch_scc0 .LBB0_2899
	s_barrier

.LBB0_3116:
	v_add_u32_e32 v142, s26, v144
	ds_read_b128 v[146:149], v142
	ds_read_b128 v[150:153], v142 offset:1024
	ds_read_b128 v[154:157], v142 offset:2048
	ds_read_b128 v[158:161], v142 offset:3072
	v_add_u32_e32 v142, s40, v144
	ds_read_b128 v[162:165], v142
	ds_read_b128 v[166:169], v142 offset:1024
	ds_read_b128 v[170:173], v142 offset:2048
	ds_read_b128 v[174:177], v142 offset:3072
	s_add_u32 s18, s34, 0xfff80080
	s_addc_u32 s19, s35, -1
	s_cmp_eq_u32 s74, 28
	s_cselect_b32 s39, s13, s19
	s_cselect_b32 s38, s69, s18
	s_cselect_b32 s19, s11, s73
	s_cselect_b32 s18, s70, s71
	v_lshl_add_u64 v[142:143], s[34:35], 0, v[138:139]
	s_add_i32 m0, s43, 0xc000
	ds_read_b128 v[178:181], v145
	ds_read_b128 v[182:185], v145 offset:1024
	ds_read_b128 v[186:189], v145 offset:2048
	ds_read_b128 v[190:193], v145 offset:3072
	ds_read_b128 v[194:197], v145 offset:4096
	ds_read_b128 v[198:201], v145 offset:5120
	ds_read_b128 v[202:205], v145 offset:6144
	ds_read_b128 v[206:209], v145 offset:7168
	global_load_lds_dwordx4 v[142:143], off
	v_lshl_add_u64 v[142:143], s[34:35], 0, v[140:141]
	s_add_i32 m0, s43, 0xe000
	s_nop 0
	global_load_lds_dwordx4 v[142:143], off
	s_waitcnt vmcnt(8)
	s_waitcnt lgkmcnt(0)
	s_barrier
	s_setprio 1
	s_waitcnt lgkmcnt(0)
	v_mfma_f32_16x16x32_bf16 v[128:131], v[146:149], v[178:181], v[128:131]
	v_mfma_f32_16x16x32_bf16 v[128:131], v[150:153], v[182:185], v[128:131]
	v_mfma_f32_16x16x32_bf16 v[120:123], v[154:157], v[178:181], v[120:123]
	v_mfma_f32_16x16x32_bf16 v[120:123], v[158:161], v[182:185], v[120:123]
	v_mfma_f32_16x16x32_bf16 v[124:127], v[162:165], v[178:181], v[124:127]
	v_mfma_f32_16x16x32_bf16 v[124:127], v[166:169], v[182:185], v[124:127]
	v_mfma_f32_16x16x32_bf16 v[116:119], v[170:173], v[178:181], v[116:119]
	v_mfma_f32_16x16x32_bf16 v[116:119], v[174:177], v[182:185], v[116:119]
	v_mfma_f32_16x16x32_bf16 v[100:103], v[170:173], v[186:189], v[100:103]
	v_mfma_f32_16x16x32_bf16 v[100:103], v[174:177], v[190:193], v[100:103]
	v_mfma_f32_16x16x32_bf16 v[108:111], v[162:165], v[186:189], v[108:111]
	v_mfma_f32_16x16x32_bf16 v[108:111], v[166:169], v[190:193], v[108:111]
	v_mfma_f32_16x16x32_bf16 v[104:107], v[154:157], v[186:189], v[104:107]
	v_mfma_f32_16x16x32_bf16 v[104:107], v[158:161], v[190:193], v[104:107]
	v_mfma_f32_16x16x32_bf16 v[112:115], v[146:149], v[186:189], v[112:115]
	v_mfma_f32_16x16x32_bf16 v[112:115], v[150:153], v[190:193], v[112:115]
	s_setprio 0
	s_setprio 1
	v_mfma_f32_16x16x32_bf16 v[96:99], v[146:149], v[194:197], v[96:99]
	v_mfma_f32_16x16x32_bf16 v[96:99], v[150:153], v[198:201], v[96:99]
	v_mfma_f32_16x16x32_bf16 v[88:91], v[154:157], v[194:197], v[88:91]
	v_mfma_f32_16x16x32_bf16 v[88:91], v[158:161], v[198:201], v[88:91]
	v_mfma_f32_16x16x32_bf16 v[92:95], v[162:165], v[194:197], v[92:95]
	v_mfma_f32_16x16x32_bf16 v[92:95], v[166:169], v[198:201], v[92:95]
	v_mfma_f32_16x16x32_bf16 v[84:87], v[170:173], v[194:197], v[84:87]
	v_mfma_f32_16x16x32_bf16 v[84:87], v[174:177], v[198:201], v[84:87]
	v_mfma_f32_16x16x32_bf16 v[68:71], v[170:173], v[202:205], v[68:71]
	v_mfma_f32_16x16x32_bf16 v[68:71], v[174:177], v[206:209], v[68:71]
	v_mfma_f32_16x16x32_bf16 v[76:79], v[162:165], v[202:205], v[76:79]
	v_mfma_f32_16x16x32_bf16 v[76:79], v[166:169], v[206:209], v[76:79]
	v_mfma_f32_16x16x32_bf16 v[72:75], v[154:157], v[202:205], v[72:75]
	v_mfma_f32_16x16x32_bf16 v[72:75], v[158:161], v[206:209], v[72:75]
	v_mfma_f32_16x16x32_bf16 v[80:83], v[146:149], v[202:205], v[80:83]
	v_mfma_f32_16x16x32_bf16 v[80:83], v[150:153], v[206:209], v[80:83]
	s_setprio 0
	s_barrier
	s_mov_b32 m0, s27
	v_lshl_add_u64 v[142:143], s[18:19], 0, v[2:3]
	s_add_u32 s76, s18, 0x80000
	ds_read_b128 v[178:181], v145 offset:16384
	ds_read_b128 v[182:185], v145 offset:17408
	ds_read_b128 v[186:189], v145 offset:18432
	ds_read_b128 v[190:193], v145 offset:19456
	ds_read_b128 v[194:197], v145 offset:20480
	ds_read_b128 v[198:201], v145 offset:21504
	ds_read_b128 v[202:205], v145 offset:22528
	ds_read_b128 v[206:209], v145 offset:23552
	global_load_lds_dwordx4 v[142:143], off
	v_lshl_add_u64 v[210:211], s[18:19], 0, v[132:133]
	s_mov_b32 m0, s37
	s_addc_u32 s77, s19, 0
	global_load_lds_dwordx4 v[210:211], off
	v_lshl_add_u64 v[212:213], s[76:77], 0, v[2:3]
	s_mov_b32 m0, s41
	v_lshl_add_u64 v[214:215], s[38:39], 0, v[134:135]
	global_load_lds_dwordx4 v[212:213], off
	v_lshl_add_u64 v[212:213], s[76:77], 0, v[132:133]
	s_mov_b32 m0, s42
	s_nop 0
	global_load_lds_dwordx4 v[212:213], off
	v_lshl_add_u64 v[212:213], s[38:39], 0, v[136:137]
	s_mov_b32 m0, s43
	s_nop 0
	global_load_lds_dwordx4 v[212:213], off
	s_mov_b32 m0, s44
	s_nop 0
	global_load_lds_dwordx4 v[214:215], off
	s_waitcnt vmcnt(8)
	s_waitcnt lgkmcnt(0)
	s_barrier
	s_setprio 1
	s_waitcnt lgkmcnt(0)
	v_mfma_f32_16x16x32_bf16 v[64:67], v[146:149], v[178:181], v[64:67]
	v_mfma_f32_16x16x32_bf16 v[64:67], v[150:153], v[182:185], v[64:67]
	v_mfma_f32_16x16x32_bf16 v[56:59], v[154:157], v[178:181], v[56:59]
	v_mfma_f32_16x16x32_bf16 v[56:59], v[158:161], v[182:185], v[56:59]
	v_mfma_f32_16x16x32_bf16 v[60:63], v[162:165], v[178:181], v[60:63]
	v_mfma_f32_16x16x32_bf16 v[60:63], v[166:169], v[182:185], v[60:63]
	v_mfma_f32_16x16x32_bf16 v[52:55], v[170:173], v[178:181], v[52:55]
	v_mfma_f32_16x16x32_bf16 v[52:55], v[174:177], v[182:185], v[52:55]
	v_mfma_f32_16x16x32_bf16 v[36:39], v[170:173], v[186:189], v[36:39]
	v_mfma_f32_16x16x32_bf16 v[36:39], v[174:177], v[190:193], v[36:39]
	v_mfma_f32_16x16x32_bf16 v[44:47], v[162:165], v[186:189], v[44:47]
	v_mfma_f32_16x16x32_bf16 v[44:47], v[166:169], v[190:193], v[44:47]
	v_mfma_f32_16x16x32_bf16 v[40:43], v[154:157], v[186:189], v[40:43]
	v_mfma_f32_16x16x32_bf16 v[40:43], v[158:161], v[190:193], v[40:43]
	v_mfma_f32_16x16x32_bf16 v[48:51], v[146:149], v[186:189], v[48:51]
	v_mfma_f32_16x16x32_bf16 v[48:51], v[150:153], v[190:193], v[48:51]
	s_setprio 0
	s_setprio 1
	v_mfma_f32_16x16x32_bf16 v[32:35], v[146:149], v[194:197], v[32:35]
	v_mfma_f32_16x16x32_bf16 v[32:35], v[150:153], v[198:201], v[32:35]
	v_mfma_f32_16x16x32_bf16 v[24:27], v[154:157], v[194:197], v[24:27]
	v_mfma_f32_16x16x32_bf16 v[24:27], v[158:161], v[198:201], v[24:27]
	v_mfma_f32_16x16x32_bf16 v[28:31], v[162:165], v[194:197], v[28:31]
	v_mfma_f32_16x16x32_bf16 v[28:31], v[166:169], v[198:201], v[28:31]
	v_mfma_f32_16x16x32_bf16 v[20:23], v[170:173], v[194:197], v[20:23]
	v_mfma_f32_16x16x32_bf16 v[20:23], v[174:177], v[198:201], v[20:23]
	v_mfma_f32_16x16x32_bf16 v[4:7], v[170:173], v[202:205], v[4:7]
	v_mfma_f32_16x16x32_bf16 v[4:7], v[174:177], v[206:209], v[4:7]
	v_mfma_f32_16x16x32_bf16 v[12:15], v[162:165], v[202:205], v[12:15]
	v_mfma_f32_16x16x32_bf16 v[12:15], v[166:169], v[206:209], v[12:15]
	v_mfma_f32_16x16x32_bf16 v[8:11], v[154:157], v[202:205], v[8:11]
	v_mfma_f32_16x16x32_bf16 v[8:11], v[158:161], v[206:209], v[8:11]
	v_mfma_f32_16x16x32_bf16 v[16:19], v[146:149], v[202:205], v[16:19]
	v_mfma_f32_16x16x32_bf16 v[16:19], v[150:153], v[206:209], v[16:19]
	s_setprio 0
	s_barrier
	v_add_u32_e32 v158, s49, v144
	v_add_u32_e32 v174, s56, v144
	ds_read_b128 v[146:149], v158
	ds_read_b128 v[150:153], v158 offset:1024
	ds_read_b128 v[154:157], v158 offset:2048
	ds_read_b128 v[158:161], v158 offset:3072
	ds_read_b128 v[162:165], v174
	ds_read_b128 v[166:169], v174 offset:1024
	ds_read_b128 v[170:173], v174 offset:2048
	ds_read_b128 v[174:177], v174 offset:3072
	s_add_u32 s38, s38, 0x80000
	s_addc_u32 s39, s39, 0
	s_mov_b32 m0, s45
	v_lshl_add_u64 v[216:217], s[38:39], 0, v[136:137]
	ds_read_b128 v[178:181], v145 offset:32768
	ds_read_b128 v[182:185], v145 offset:33792
	ds_read_b128 v[186:189], v145 offset:34816
	ds_read_b128 v[190:193], v145 offset:35840
	ds_read_b128 v[194:197], v145 offset:36864
	ds_read_b128 v[198:201], v145 offset:37888
	ds_read_b128 v[202:205], v145 offset:38912
	ds_read_b128 v[206:209], v145 offset:39936
	global_load_lds_dwordx4 v[216:217], off
	v_lshl_add_u64 v[216:217], s[38:39], 0, v[134:135]
	s_mov_b32 m0, s46
	s_nop 0
	global_load_lds_dwordx4 v[216:217], off
	s_waitcnt vmcnt(8)
	s_waitcnt lgkmcnt(0)
	s_barrier
	s_setprio 1
	s_waitcnt lgkmcnt(0)
	v_mfma_f32_16x16x32_bf16 v[128:131], v[146:149], v[178:181], v[128:131]
	v_mfma_f32_16x16x32_bf16 v[128:131], v[150:153], v[182:185], v[128:131]
	v_mfma_f32_16x16x32_bf16 v[120:123], v[154:157], v[178:181], v[120:123]
	v_mfma_f32_16x16x32_bf16 v[120:123], v[158:161], v[182:185], v[120:123]
	v_mfma_f32_16x16x32_bf16 v[124:127], v[162:165], v[178:181], v[124:127]
	v_mfma_f32_16x16x32_bf16 v[124:127], v[166:169], v[182:185], v[124:127]
	v_mfma_f32_16x16x32_bf16 v[116:119], v[170:173], v[178:181], v[116:119]
	v_mfma_f32_16x16x32_bf16 v[116:119], v[174:177], v[182:185], v[116:119]
	v_mfma_f32_16x16x32_bf16 v[100:103], v[170:173], v[186:189], v[100:103]
	v_mfma_f32_16x16x32_bf16 v[100:103], v[174:177], v[190:193], v[100:103]
	v_mfma_f32_16x16x32_bf16 v[108:111], v[162:165], v[186:189], v[108:111]
	v_mfma_f32_16x16x32_bf16 v[108:111], v[166:169], v[190:193], v[108:111]
	v_mfma_f32_16x16x32_bf16 v[104:107], v[154:157], v[186:189], v[104:107]
	v_mfma_f32_16x16x32_bf16 v[104:107], v[158:161], v[190:193], v[104:107]
	v_mfma_f32_16x16x32_bf16 v[112:115], v[146:149], v[186:189], v[112:115]
	v_mfma_f32_16x16x32_bf16 v[112:115], v[150:153], v[190:193], v[112:115]
	s_setprio 0
	s_setprio 1
	v_mfma_f32_16x16x32_bf16 v[96:99], v[146:149], v[194:197], v[96:99]
	v_mfma_f32_16x16x32_bf16 v[96:99], v[150:153], v[198:201], v[96:99]
	v_mfma_f32_16x16x32_bf16 v[88:91], v[154:157], v[194:197], v[88:91]
	v_mfma_f32_16x16x32_bf16 v[88:91], v[158:161], v[198:201], v[88:91]
	v_mfma_f32_16x16x32_bf16 v[92:95], v[162:165], v[194:197], v[92:95]
	v_mfma_f32_16x16x32_bf16 v[92:95], v[166:169], v[198:201], v[92:95]
	v_mfma_f32_16x16x32_bf16 v[84:87], v[170:173], v[194:197], v[84:87]
	v_mfma_f32_16x16x32_bf16 v[84:87], v[174:177], v[198:201], v[84:87]
	v_mfma_f32_16x16x32_bf16 v[68:71], v[170:173], v[202:205], v[68:71]
	v_mfma_f32_16x16x32_bf16 v[68:71], v[174:177], v[206:209], v[68:71]
	v_mfma_f32_16x16x32_bf16 v[76:79], v[162:165], v[202:205], v[76:79]
	v_mfma_f32_16x16x32_bf16 v[76:79], v[166:169], v[206:209], v[76:79]
	v_mfma_f32_16x16x32_bf16 v[72:75], v[154:157], v[202:205], v[72:75]
	v_mfma_f32_16x16x32_bf16 v[72:75], v[158:161], v[206:209], v[72:75]
	v_mfma_f32_16x16x32_bf16 v[80:83], v[146:149], v[202:205], v[80:83]
	v_mfma_f32_16x16x32_bf16 v[80:83], v[150:153], v[206:209], v[80:83]
	s_setprio 0
	s_barrier
	s_mov_b32 m0, s50
	v_lshl_add_u64 v[142:143], v[142:143], 0, s[64:65]
	s_add_u32 s18, s18, 0x80080
	ds_read_b128 v[178:181], v145 offset:49152
	ds_read_b128 v[182:185], v145 offset:50176
	ds_read_b128 v[186:189], v145 offset:51200
	ds_read_b128 v[190:193], v145 offset:52224
	ds_read_b128 v[194:197], v145 offset:53248
	ds_read_b128 v[198:201], v145 offset:54272
	ds_read_b128 v[202:205], v145 offset:55296
	ds_read_b128 v[206:209], v145 offset:56320
	global_load_lds_dwordx4 v[142:143], off
	v_lshl_add_u64 v[142:143], v[210:211], 0, s[64:65]
	s_mov_b32 m0, s51
	s_addc_u32 s19, s19, 0
	global_load_lds_dwordx4 v[142:143], off
	v_lshl_add_u64 v[142:143], s[18:19], 0, v[2:3]
	s_mov_b32 m0, s57
	s_nop 0
	global_load_lds_dwordx4 v[142:143], off
	v_lshl_add_u64 v[142:143], s[18:19], 0, v[132:133]
	s_mov_b32 m0, s58
	s_nop 0
	global_load_lds_dwordx4 v[142:143], off
	v_lshl_add_u64 v[142:143], v[212:213], 0, s[64:65]
	s_mov_b32 m0, s52
	s_nop 0
	global_load_lds_dwordx4 v[142:143], off
	v_lshl_add_u64 v[142:143], v[214:215], 0, s[64:65]
	s_mov_b32 m0, s53
	s_nop 0
	global_load_lds_dwordx4 v[142:143], off
	s_waitcnt vmcnt(8)
	s_waitcnt lgkmcnt(0)
	s_barrier
	s_setprio 1
	s_waitcnt lgkmcnt(0)
	v_mfma_f32_16x16x32_bf16 v[64:67], v[146:149], v[178:181], v[64:67]
	v_mfma_f32_16x16x32_bf16 v[64:67], v[150:153], v[182:185], v[64:67]
	v_mfma_f32_16x16x32_bf16 v[56:59], v[154:157], v[178:181], v[56:59]
	v_mfma_f32_16x16x32_bf16 v[56:59], v[158:161], v[182:185], v[56:59]
	v_mfma_f32_16x16x32_bf16 v[60:63], v[162:165], v[178:181], v[60:63]
	v_mfma_f32_16x16x32_bf16 v[60:63], v[166:169], v[182:185], v[60:63]
	v_mfma_f32_16x16x32_bf16 v[52:55], v[170:173], v[178:181], v[52:55]
	v_mfma_f32_16x16x32_bf16 v[52:55], v[174:177], v[182:185], v[52:55]
	v_mfma_f32_16x16x32_bf16 v[36:39], v[170:173], v[186:189], v[36:39]
	v_mfma_f32_16x16x32_bf16 v[36:39], v[174:177], v[190:193], v[36:39]
	v_mfma_f32_16x16x32_bf16 v[44:47], v[162:165], v[186:189], v[44:47]
	v_mfma_f32_16x16x32_bf16 v[44:47], v[166:169], v[190:193], v[44:47]
	v_mfma_f32_16x16x32_bf16 v[40:43], v[154:157], v[186:189], v[40:43]
	v_mfma_f32_16x16x32_bf16 v[40:43], v[158:161], v[190:193], v[40:43]
	v_mfma_f32_16x16x32_bf16 v[48:51], v[146:149], v[186:189], v[48:51]
	v_mfma_f32_16x16x32_bf16 v[48:51], v[150:153], v[190:193], v[48:51]
	s_setprio 0
	s_setprio 1
	v_mfma_f32_16x16x32_bf16 v[32:35], v[146:149], v[194:197], v[32:35]
	v_mfma_f32_16x16x32_bf16 v[32:35], v[150:153], v[198:201], v[32:35]
	v_mfma_f32_16x16x32_bf16 v[24:27], v[154:157], v[194:197], v[24:27]
	v_mfma_f32_16x16x32_bf16 v[24:27], v[158:161], v[198:201], v[24:27]
	v_mfma_f32_16x16x32_bf16 v[28:31], v[162:165], v[194:197], v[28:31]
	v_mfma_f32_16x16x32_bf16 v[28:31], v[166:169], v[198:201], v[28:31]
	v_mfma_f32_16x16x32_bf16 v[20:23], v[170:173], v[194:197], v[20:23]
	v_mfma_f32_16x16x32_bf16 v[20:23], v[174:177], v[198:201], v[20:23]
	v_mfma_f32_16x16x32_bf16 v[4:7], v[170:173], v[202:205], v[4:7]
	v_mfma_f32_16x16x32_bf16 v[4:7], v[174:177], v[206:209], v[4:7]
	v_mfma_f32_16x16x32_bf16 v[12:15], v[162:165], v[202:205], v[12:15]
	v_mfma_f32_16x16x32_bf16 v[12:15], v[166:169], v[206:209], v[12:15]
	v_mfma_f32_16x16x32_bf16 v[8:11], v[154:157], v[202:205], v[8:11]
	v_mfma_f32_16x16x32_bf16 v[8:11], v[158:161], v[206:209], v[8:11]
	v_mfma_f32_16x16x32_bf16 v[16:19], v[146:149], v[202:205], v[16:19]
	v_mfma_f32_16x16x32_bf16 v[16:19], v[150:153], v[206:209], v[16:19]
	s_setprio 0
	s_barrier
	s_add_i32 s74, s74, 2
	s_add_u32 s34, s34, 0x100
	s_addc_u32 s35, s35, 0
	s_add_u32 s71, s71, 0x100
	s_addc_u32 s73, s73, 0
	s_cmp_gt_u32 s74, 29
	s_cbranch_scc0 .LBB0_3116
	s_and_b64 vcc, exec, s[8:9]
	s_cbranch_vccz .LBB0_3119
	s_barrier

.LBB0_3195:
	v_add_u32_e32 v144, s26, v249
	v_add_u32_e32 v160, s38, v249
	ds_read_b128 v[132:135], v144
	ds_read_b128 v[136:139], v144 offset:1024
	ds_read_b128 v[140:143], v144 offset:2048
	ds_read_b128 v[144:147], v144 offset:3072
	ds_read_b128 v[148:151], v160
	ds_read_b128 v[152:155], v160 offset:1024
	ds_read_b128 v[156:159], v160 offset:2048
	ds_read_b128 v[160:163], v160 offset:3072
	s_add_u32 s24, s14, 0x100
	s_addc_u32 s25, s15, 0
	s_cmpk_eq_i32 s74, 0x54
	s_cselect_b32 s35, s5, s25
	s_cselect_b32 s34, s4, s24
	s_cselect_b32 s19, s13, s73
	s_cselect_b32 s18, s12, s71
	v_lshl_add_u64 v[196:197], s[14:15], 0, v[222:223]
	s_add_i32 m0, s41, 0xc000
	ds_read_b128 v[164:167], v250
	ds_read_b128 v[168:171], v250 offset:1024
	ds_read_b128 v[172:175], v250 offset:2048
	ds_read_b128 v[176:179], v250 offset:3072
	ds_read_b128 v[180:183], v250 offset:4096
	ds_read_b128 v[184:187], v250 offset:5120
	ds_read_b128 v[188:191], v250 offset:6144
	ds_read_b128 v[192:195], v250 offset:7168
	global_load_lds_dwordx4 v[196:197], off
	v_lshl_add_u64 v[196:197], s[14:15], 0, v[224:225]
	s_add_i32 m0, s41, 0xe000
	s_nop 0
	global_load_lds_dwordx4 v[196:197], off
	s_waitcnt vmcnt(8)
	s_waitcnt lgkmcnt(0)
	s_barrier
	s_setprio 1
	s_waitcnt lgkmcnt(0)
	v_mfma_f32_16x16x32_bf16 v[128:131], v[132:135], v[164:167], v[128:131]
	v_mfma_f32_16x16x32_bf16 v[128:131], v[136:139], v[168:171], v[128:131]
	v_mfma_f32_16x16x32_bf16 v[124:127], v[140:143], v[164:167], v[124:127]
	v_mfma_f32_16x16x32_bf16 v[124:127], v[144:147], v[168:171], v[124:127]
	v_mfma_f32_16x16x32_bf16 v[120:123], v[148:151], v[164:167], v[120:123]
	v_mfma_f32_16x16x32_bf16 v[120:123], v[152:155], v[168:171], v[120:123]
	v_mfma_f32_16x16x32_bf16 v[116:119], v[156:159], v[164:167], v[116:119]
	v_mfma_f32_16x16x32_bf16 v[116:119], v[160:163], v[168:171], v[116:119]
	v_mfma_f32_16x16x32_bf16 v[100:103], v[156:159], v[172:175], v[100:103]
	v_mfma_f32_16x16x32_bf16 v[100:103], v[160:163], v[176:179], v[100:103]
	v_mfma_f32_16x16x32_bf16 v[104:107], v[148:151], v[172:175], v[104:107]
	v_mfma_f32_16x16x32_bf16 v[104:107], v[152:155], v[176:179], v[104:107]
	v_mfma_f32_16x16x32_bf16 v[108:111], v[140:143], v[172:175], v[108:111]
	v_mfma_f32_16x16x32_bf16 v[108:111], v[144:147], v[176:179], v[108:111]
	v_mfma_f32_16x16x32_bf16 v[112:115], v[132:135], v[172:175], v[112:115]
	v_mfma_f32_16x16x32_bf16 v[112:115], v[136:139], v[176:179], v[112:115]
	s_setprio 0
	s_setprio 1
	v_mfma_f32_16x16x32_bf16 v[96:99], v[132:135], v[180:183], v[96:99]
	v_mfma_f32_16x16x32_bf16 v[96:99], v[136:139], v[184:187], v[96:99]
	v_mfma_f32_16x16x32_bf16 v[92:95], v[140:143], v[180:183], v[92:95]
	v_mfma_f32_16x16x32_bf16 v[92:95], v[144:147], v[184:187], v[92:95]
	v_mfma_f32_16x16x32_bf16 v[88:91], v[148:151], v[180:183], v[88:91]
	v_mfma_f32_16x16x32_bf16 v[88:91], v[152:155], v[184:187], v[88:91]
	v_mfma_f32_16x16x32_bf16 v[84:87], v[156:159], v[180:183], v[84:87]
	v_mfma_f32_16x16x32_bf16 v[84:87], v[160:163], v[184:187], v[84:87]
	v_mfma_f32_16x16x32_bf16 v[68:71], v[156:159], v[188:191], v[68:71]
	v_mfma_f32_16x16x32_bf16 v[68:71], v[160:163], v[192:195], v[68:71]
	v_mfma_f32_16x16x32_bf16 v[72:75], v[148:151], v[188:191], v[72:75]
	v_mfma_f32_16x16x32_bf16 v[72:75], v[152:155], v[192:195], v[72:75]
	v_mfma_f32_16x16x32_bf16 v[76:79], v[140:143], v[188:191], v[76:79]
	v_mfma_f32_16x16x32_bf16 v[76:79], v[144:147], v[192:195], v[76:79]
	v_mfma_f32_16x16x32_bf16 v[80:83], v[132:135], v[188:191], v[80:83]
	v_mfma_f32_16x16x32_bf16 v[80:83], v[136:139], v[192:195], v[80:83]
	s_setprio 0
	s_barrier
	s_mov_b32 m0, s27
	v_lshl_add_u64 v[196:197], s[18:19], 0, v[2:3]
	s_add_u32 s14, s18, 0x160000
	ds_read_b128 v[164:167], v250 offset:16384
	ds_read_b128 v[168:171], v250 offset:17408
	ds_read_b128 v[172:175], v250 offset:18432
	ds_read_b128 v[176:179], v250 offset:19456
	ds_read_b128 v[180:183], v250 offset:20480
	ds_read_b128 v[184:187], v250 offset:21504
	ds_read_b128 v[188:191], v250 offset:22528
	ds_read_b128 v[192:195], v250 offset:23552
	global_load_lds_dwordx4 v[196:197], off
	v_lshl_add_u64 v[198:199], s[18:19], 0, v[216:217]
	s_mov_b32 m0, s37
	s_addc_u32 s15, s19, 0
	global_load_lds_dwordx4 v[198:199], off
	v_lshl_add_u64 v[200:201], s[14:15], 0, v[2:3]
	s_mov_b32 m0, s39
	v_lshl_add_u64 v[202:203], s[34:35], 0, v[218:219]
	global_load_lds_dwordx4 v[200:201], off
	v_lshl_add_u64 v[200:201], s[14:15], 0, v[216:217]
	s_mov_b32 m0, s40
	s_nop 0
	global_load_lds_dwordx4 v[200:201], off
	v_lshl_add_u64 v[200:201], s[34:35], 0, v[220:221]
	s_mov_b32 m0, s41
	s_nop 0
	global_load_lds_dwordx4 v[200:201], off
	s_mov_b32 m0, s42
	s_nop 0
	global_load_lds_dwordx4 v[202:203], off
	s_waitcnt vmcnt(8)
	s_waitcnt lgkmcnt(0)
	s_barrier
	s_setprio 1
	s_waitcnt lgkmcnt(0)
	v_mfma_f32_16x16x32_bf16 v[64:67], v[132:135], v[164:167], v[64:67]
	v_mfma_f32_16x16x32_bf16 v[64:67], v[136:139], v[168:171], v[64:67]
	v_mfma_f32_16x16x32_bf16 v[60:63], v[140:143], v[164:167], v[60:63]
	v_mfma_f32_16x16x32_bf16 v[60:63], v[144:147], v[168:171], v[60:63]
	v_mfma_f32_16x16x32_bf16 v[56:59], v[148:151], v[164:167], v[56:59]
	v_mfma_f32_16x16x32_bf16 v[56:59], v[152:155], v[168:171], v[56:59]
	v_mfma_f32_16x16x32_bf16 v[52:55], v[156:159], v[164:167], v[52:55]
	v_mfma_f32_16x16x32_bf16 v[52:55], v[160:163], v[168:171], v[52:55]
	v_mfma_f32_16x16x32_bf16 v[36:39], v[156:159], v[172:175], v[36:39]
	v_mfma_f32_16x16x32_bf16 v[36:39], v[160:163], v[176:179], v[36:39]
	v_mfma_f32_16x16x32_bf16 v[40:43], v[148:151], v[172:175], v[40:43]
	v_mfma_f32_16x16x32_bf16 v[40:43], v[152:155], v[176:179], v[40:43]
	v_mfma_f32_16x16x32_bf16 v[44:47], v[140:143], v[172:175], v[44:47]
	v_mfma_f32_16x16x32_bf16 v[44:47], v[144:147], v[176:179], v[44:47]
	v_mfma_f32_16x16x32_bf16 v[48:51], v[132:135], v[172:175], v[48:51]
	v_mfma_f32_16x16x32_bf16 v[48:51], v[136:139], v[176:179], v[48:51]
	s_setprio 0
	s_setprio 1
	v_mfma_f32_16x16x32_bf16 v[32:35], v[132:135], v[180:183], v[32:35]
	v_mfma_f32_16x16x32_bf16 v[32:35], v[136:139], v[184:187], v[32:35]
	v_mfma_f32_16x16x32_bf16 v[28:31], v[140:143], v[180:183], v[28:31]
	v_mfma_f32_16x16x32_bf16 v[28:31], v[144:147], v[184:187], v[28:31]
	v_mfma_f32_16x16x32_bf16 v[24:27], v[148:151], v[180:183], v[24:27]
	v_mfma_f32_16x16x32_bf16 v[24:27], v[152:155], v[184:187], v[24:27]
	v_mfma_f32_16x16x32_bf16 v[20:23], v[156:159], v[180:183], v[20:23]
	v_mfma_f32_16x16x32_bf16 v[20:23], v[160:163], v[184:187], v[20:23]
	v_mfma_f32_16x16x32_bf16 v[4:7], v[156:159], v[188:191], v[4:7]
	v_mfma_f32_16x16x32_bf16 v[4:7], v[160:163], v[192:195], v[4:7]
	v_mfma_f32_16x16x32_bf16 v[8:11], v[148:151], v[188:191], v[8:11]
	v_mfma_f32_16x16x32_bf16 v[8:11], v[152:155], v[192:195], v[8:11]
	v_mfma_f32_16x16x32_bf16 v[12:15], v[140:143], v[188:191], v[12:15]
	v_mfma_f32_16x16x32_bf16 v[12:15], v[144:147], v[192:195], v[12:15]
	v_mfma_f32_16x16x32_bf16 v[16:19], v[132:135], v[188:191], v[16:19]
	v_mfma_f32_16x16x32_bf16 v[16:19], v[136:139], v[192:195], v[16:19]
	s_setprio 0
	s_barrier
	v_add_u32_e32 v144, s49, v249
	v_add_u32_e32 v160, s56, v249
	ds_read_b128 v[132:135], v144
	ds_read_b128 v[136:139], v144 offset:1024
	ds_read_b128 v[140:143], v144 offset:2048
	ds_read_b128 v[144:147], v144 offset:3072
	ds_read_b128 v[148:151], v160
	ds_read_b128 v[152:155], v160 offset:1024
	ds_read_b128 v[156:159], v160 offset:2048
	ds_read_b128 v[160:163], v160 offset:3072
	s_add_u32 s14, s34, 0x160000
	s_addc_u32 s15, s35, 0
	s_mov_b32 m0, s43
	v_lshl_add_u64 v[204:205], s[14:15], 0, v[220:221]
	ds_read_b128 v[164:167], v250 offset:32768
	ds_read_b128 v[168:171], v250 offset:33792
	ds_read_b128 v[172:175], v250 offset:34816
	ds_read_b128 v[176:179], v250 offset:35840
	ds_read_b128 v[180:183], v250 offset:36864
	ds_read_b128 v[184:187], v250 offset:37888
	ds_read_b128 v[188:191], v250 offset:38912
	ds_read_b128 v[192:195], v250 offset:39936
	global_load_lds_dwordx4 v[204:205], off
	v_lshl_add_u64 v[204:205], s[14:15], 0, v[218:219]
	s_mov_b32 m0, s44
	s_nop 0
	global_load_lds_dwordx4 v[204:205], off
	s_waitcnt vmcnt(8)
	s_waitcnt lgkmcnt(0)
	s_barrier
	s_setprio 1
	s_waitcnt lgkmcnt(0)
	v_mfma_f32_16x16x32_bf16 v[128:131], v[132:135], v[164:167], v[128:131]
	v_mfma_f32_16x16x32_bf16 v[128:131], v[136:139], v[168:171], v[128:131]
	v_mfma_f32_16x16x32_bf16 v[124:127], v[140:143], v[164:167], v[124:127]
	v_mfma_f32_16x16x32_bf16 v[124:127], v[144:147], v[168:171], v[124:127]
	v_mfma_f32_16x16x32_bf16 v[120:123], v[148:151], v[164:167], v[120:123]
	v_mfma_f32_16x16x32_bf16 v[120:123], v[152:155], v[168:171], v[120:123]
	v_mfma_f32_16x16x32_bf16 v[116:119], v[156:159], v[164:167], v[116:119]
	v_mfma_f32_16x16x32_bf16 v[116:119], v[160:163], v[168:171], v[116:119]
	v_mfma_f32_16x16x32_bf16 v[100:103], v[156:159], v[172:175], v[100:103]
	v_mfma_f32_16x16x32_bf16 v[100:103], v[160:163], v[176:179], v[100:103]
	v_mfma_f32_16x16x32_bf16 v[104:107], v[148:151], v[172:175], v[104:107]
	v_mfma_f32_16x16x32_bf16 v[104:107], v[152:155], v[176:179], v[104:107]
	v_mfma_f32_16x16x32_bf16 v[108:111], v[140:143], v[172:175], v[108:111]
	v_mfma_f32_16x16x32_bf16 v[108:111], v[144:147], v[176:179], v[108:111]
	v_mfma_f32_16x16x32_bf16 v[112:115], v[132:135], v[172:175], v[112:115]
	v_mfma_f32_16x16x32_bf16 v[112:115], v[136:139], v[176:179], v[112:115]
	s_setprio 0
	s_setprio 1
	v_mfma_f32_16x16x32_bf16 v[96:99], v[132:135], v[180:183], v[96:99]
	v_mfma_f32_16x16x32_bf16 v[96:99], v[136:139], v[184:187], v[96:99]
	v_mfma_f32_16x16x32_bf16 v[92:95], v[140:143], v[180:183], v[92:95]
	v_mfma_f32_16x16x32_bf16 v[92:95], v[144:147], v[184:187], v[92:95]
	v_mfma_f32_16x16x32_bf16 v[88:91], v[148:151], v[180:183], v[88:91]
	v_mfma_f32_16x16x32_bf16 v[88:91], v[152:155], v[184:187], v[88:91]
	v_mfma_f32_16x16x32_bf16 v[84:87], v[156:159], v[180:183], v[84:87]
	v_mfma_f32_16x16x32_bf16 v[84:87], v[160:163], v[184:187], v[84:87]
	v_mfma_f32_16x16x32_bf16 v[68:71], v[156:159], v[188:191], v[68:71]
	v_mfma_f32_16x16x32_bf16 v[68:71], v[160:163], v[192:195], v[68:71]
	v_mfma_f32_16x16x32_bf16 v[72:75], v[148:151], v[188:191], v[72:75]
	v_mfma_f32_16x16x32_bf16 v[72:75], v[152:155], v[192:195], v[72:75]
	v_mfma_f32_16x16x32_bf16 v[76:79], v[140:143], v[188:191], v[76:79]
	v_mfma_f32_16x16x32_bf16 v[76:79], v[144:147], v[192:195], v[76:79]
	v_mfma_f32_16x16x32_bf16 v[80:83], v[132:135], v[188:191], v[80:83]
	v_mfma_f32_16x16x32_bf16 v[80:83], v[136:139], v[192:195], v[80:83]
	s_setprio 0
	s_barrier
	s_mov_b32 m0, s50
	v_lshl_add_u64 v[196:197], v[196:197], 0, s[64:65]
	s_add_u32 s14, s18, 0x160080
	ds_read_b128 v[164:167], v250 offset:49152
	ds_read_b128 v[168:171], v250 offset:50176
	ds_read_b128 v[172:175], v250 offset:51200
	ds_read_b128 v[176:179], v250 offset:52224
	ds_read_b128 v[180:183], v250 offset:53248
	ds_read_b128 v[184:187], v250 offset:54272
	ds_read_b128 v[188:191], v250 offset:55296
	ds_read_b128 v[192:195], v250 offset:56320
	global_load_lds_dwordx4 v[196:197], off
	v_lshl_add_u64 v[196:197], v[198:199], 0, s[64:65]
	s_mov_b32 m0, s51
	s_addc_u32 s15, s19, 0
	global_load_lds_dwordx4 v[196:197], off
	v_lshl_add_u64 v[196:197], s[14:15], 0, v[2:3]
	s_mov_b32 m0, s57
	s_nop 0
	global_load_lds_dwordx4 v[196:197], off
	v_lshl_add_u64 v[196:197], s[14:15], 0, v[216:217]
	s_mov_b32 m0, s58
	s_nop 0
	global_load_lds_dwordx4 v[196:197], off
	v_lshl_add_u64 v[196:197], v[200:201], 0, s[64:65]
	s_mov_b32 m0, s52
	s_nop 0
	global_load_lds_dwordx4 v[196:197], off
	v_lshl_add_u64 v[196:197], v[202:203], 0, s[64:65]
	s_mov_b32 m0, s53
	s_nop 0
	global_load_lds_dwordx4 v[196:197], off
	s_waitcnt vmcnt(8)
	s_waitcnt lgkmcnt(0)
	s_barrier
	s_setprio 1
	s_waitcnt lgkmcnt(0)
	v_mfma_f32_16x16x32_bf16 v[64:67], v[132:135], v[164:167], v[64:67]
	v_mfma_f32_16x16x32_bf16 v[64:67], v[136:139], v[168:171], v[64:67]
	v_mfma_f32_16x16x32_bf16 v[60:63], v[140:143], v[164:167], v[60:63]
	v_mfma_f32_16x16x32_bf16 v[60:63], v[144:147], v[168:171], v[60:63]
	v_mfma_f32_16x16x32_bf16 v[56:59], v[148:151], v[164:167], v[56:59]
	v_mfma_f32_16x16x32_bf16 v[56:59], v[152:155], v[168:171], v[56:59]
	v_mfma_f32_16x16x32_bf16 v[52:55], v[156:159], v[164:167], v[52:55]
	v_mfma_f32_16x16x32_bf16 v[52:55], v[160:163], v[168:171], v[52:55]
	v_mfma_f32_16x16x32_bf16 v[36:39], v[156:159], v[172:175], v[36:39]
	v_mfma_f32_16x16x32_bf16 v[36:39], v[160:163], v[176:179], v[36:39]
	v_mfma_f32_16x16x32_bf16 v[40:43], v[148:151], v[172:175], v[40:43]
	v_mfma_f32_16x16x32_bf16 v[40:43], v[152:155], v[176:179], v[40:43]
	v_mfma_f32_16x16x32_bf16 v[44:47], v[140:143], v[172:175], v[44:47]
	v_mfma_f32_16x16x32_bf16 v[44:47], v[144:147], v[176:179], v[44:47]
	v_mfma_f32_16x16x32_bf16 v[48:51], v[132:135], v[172:175], v[48:51]
	v_mfma_f32_16x16x32_bf16 v[48:51], v[136:139], v[176:179], v[48:51]
	s_setprio 0
	s_setprio 1
	v_mfma_f32_16x16x32_bf16 v[32:35], v[132:135], v[180:183], v[32:35]
	v_mfma_f32_16x16x32_bf16 v[32:35], v[136:139], v[184:187], v[32:35]
	v_mfma_f32_16x16x32_bf16 v[28:31], v[140:143], v[180:183], v[28:31]
	v_mfma_f32_16x16x32_bf16 v[28:31], v[144:147], v[184:187], v[28:31]
	v_mfma_f32_16x16x32_bf16 v[24:27], v[148:151], v[180:183], v[24:27]
	v_mfma_f32_16x16x32_bf16 v[24:27], v[152:155], v[184:187], v[24:27]
	v_mfma_f32_16x16x32_bf16 v[20:23], v[156:159], v[180:183], v[20:23]
	v_mfma_f32_16x16x32_bf16 v[20:23], v[160:163], v[184:187], v[20:23]
	v_mfma_f32_16x16x32_bf16 v[4:7], v[156:159], v[188:191], v[4:7]
	v_mfma_f32_16x16x32_bf16 v[4:7], v[160:163], v[192:195], v[4:7]
	v_mfma_f32_16x16x32_bf16 v[8:11], v[148:151], v[188:191], v[8:11]
	v_mfma_f32_16x16x32_bf16 v[8:11], v[152:155], v[192:195], v[8:11]
	v_mfma_f32_16x16x32_bf16 v[12:15], v[140:143], v[188:191], v[12:15]
	v_mfma_f32_16x16x32_bf16 v[12:15], v[144:147], v[192:195], v[12:15]
	v_mfma_f32_16x16x32_bf16 v[16:19], v[132:135], v[188:191], v[16:19]
	v_mfma_f32_16x16x32_bf16 v[16:19], v[136:139], v[192:195], v[16:19]
	s_setprio 0
	s_barrier
	s_add_i32 s74, s74, 2
	s_add_u32 s71, s71, 0x100
	s_addc_u32 s73, s73, 0
	s_cmpk_gt_u32 s74, 0x55
	s_mov_b64 s[14:15], s[24:25]
	s_cbranch_scc0 .LBB0_3195
	s_and_b64 vcc, exec, s[10:11]
	s_cbranch_vccz .LBB0_3198
	s_barrier
